# dilated and cross-attention output stores widened: adjacent 16-dim tiles paired with v_permlane16_swap, one global_store_dwordx4 instead of two dwordx2 (same bytes, same addresses)
# speedup vs baseline: 1.0020x; 1.0020x over previous
; #define LAS __attribute__((address_space(3)))
; __device__ __forceinline__ int opaque_tid() { int t = (int)threadIdx.x; asm volatile("" : "+v"(t)); return t; }
; #define XLOAD(kvbase, c8) do { const bf16_t* _src = (kvbase) + (((c8) >= 4) ? 2048 : 0) + ((c8) & 3) * 128 + piece * 8; \
;         _Pragma("unroll") for (int _it = 0; _it < 8; ++_it) pre[_it] = *(const u32x4*)(_src + (size_t)(srow + 32 * _it) * 4096); } while (0)
; #define XSTORE(buf) do { _Pragma("unroll") for (int _it = 0; _it < 8; ++_it) *(LAS u32x4*)((buf) + (srow + 32 * _it) * KV_STRIDE + piece * 16) = pre[_it]; } while (0)
; __device__ void cross_items(const Params& p, LAS unsigned char* lds) {
;     const int tid = opaque_tid(), lane = tid & 63, w = __builtin_amdgcn_readfirstlane(tid >> 6), idx = lane & 15, g = lane >> 4;
;     unsigned char* ws = p.ws;
;     bf16_t* oc = (bf16_t*)(ws + OFF_OC);
;     const unsigned lbase = (unsigned)(size_t)lds;
;     const int piece = tid & 15, srow = tid >> 4;
;     const int G = (int)gridDim.x;
;     u32x4 pre[8];
;     ...
;     const int pmx = 8 * ((int)blockIdx.x & 7) + ((int)blockIdx.x >> 5), hdx = ((int)blockIdx.x >> 3) & 3;
;     const int item0 = (pmx >> 4) * 128 + hdx * 32 + 2 * (pmx & 15);
;     { const bf16_t* kvb0 = (const bf16_t*)(ws + OFF_MKV) + (size_t)((item0 >> 7) * 256) * 4096 + ((item0 >> 5) & 3) * 512; XLOAD(kvb0, 0); }
;     for (int item = item0; item < item0 + 2; ++item) {
;         const int b = item >> 7, head = (item >> 5) & 3, qb = item & 31;
;         const size_t tok = (size_t)(b * SEQ + qb * 128 + 16 * w + idx);
;         const bf16_t* qrow = (const bf16_t*)(ws + OFF_B1) + tok * DM + head * 512 + 8 * g;
;         const bf16_t* kvb = (const bf16_t*)(ws + OFF_MKV) + (size_t)(b * 256) * 4096 + head * 512;
;         f32x4 sc[16];
; #pragma unroll
;         for (int kt = 0; kt < 16; ++kt) sc[kt] = (f32x4){0.f, 0.f, 0.f, 0.f};
;         for (int c = 0; c < 4; ++c) {
;             LAS unsigned char* buf = lds + (c & 1) * KV_BUF;
;             XSTORE(buf);
;             bf16x8 qf[4];
; #pragma unroll
;             for (int ks = 0; ks < 4; ++ks) qf[ks] = *(const bf16x8*)(qrow + c * 128 + 32 * ks);
.LBB0_391:
	s_or_b64 exec, exec, s[0:1]
	v_mov_b32_e32 v40, v212
	s_waitcnt vmcnt(0) lgkmcnt(0)
	s_barrier
	v_readlane_b32 s0, v254, 29
	v_and_b32_e32 v243, 63, v212
	v_lshrrev_b32_e32 v242, 6, v212
	s_nop 1
	v_readfirstlane_b32 s4, v242
	s_lshr_b32 s0, s0, 9
	s_and_b32 s1, s0, 7
	s_lshl_b32 s1, s1, 3
	s_lshr_b32 s2, s0, 5
	s_add_i32 s1, s1, s2
	s_lshr_b32 s2, s0, 3
	s_and_b32 s2, s2, 3
	s_lshr_b32 s3, s1, 4
	s_add_u32 s6, s92, 0x1000
	s_addc_u32 s7, s93, 0
	v_and_b32_e32 v4, 15, v243
	v_lshrrev_b32_e32 v5, 4, v243
	v_and_b32_e32 v6, 15, v212
	v_lshrrev_b32_e32 v7, 4, v212
	v_and_b32_e32 v8, 7, v7
	v_lshl_add_u32 v8, v8, 1, v6
	v_and_b32_e32 v8, 15, v8
	v_lshlrev_b32_e32 v8, 4, v8
	v_lshl_add_u32 v0, v7, 8, v8
	v_add_u32_e32 v1, 0x10000, v0
	v_and_b32_e32 v9, 7, v4
	v_lshlrev_b32_e32 v9, 1, v9
	v_add_u32_e32 v9, v9, v5
	v_add_u32_e32 v10, 0, v9
	v_and_b32_e32 v10, 15, v10
	v_lshlrev_b32_e32 v10, 4, v10
	v_lshl_add_u32 v2, v4, 8, v10
	v_add_u32_e32 v10, 4, v9
	v_and_b32_e32 v10, 15, v10
	v_lshlrev_b32_e32 v10, 4, v10
	v_lshl_add_u32 v208, v4, 8, v10
	v_add_u32_e32 v10, 8, v9
	v_and_b32_e32 v10, 15, v10
	v_lshlrev_b32_e32 v10, 4, v10
	v_lshl_add_u32 v209, v4, 8, v10
	v_add_u32_e32 v10, 12, v9
	v_and_b32_e32 v10, 15, v10
	v_lshlrev_b32_e32 v10, 4, v10
	v_lshl_add_u32 v210, v4, 8, v10
	s_lshl_b32 s5, s1, 20
	s_lshl_b32 s8, s4, 16
	s_add_i32 s5, s5, s8
	s_lshl_b32 s8, s2, 10
	s_add_i32 s5, s5, s8
	v_lshlrev_b32_e32 v246, 12, v4
	v_add_u32_e32 v246, s5, v246
	v_lshl_add_u32 v248, v5, 3, v246
	v_add_u32_e32 v248, 0xd100000, v248
	v_and_b32_e32 v8, 1, v5
	v_mul_u32_u24_e32 v8, 24, v8
	v_add_u32_e32 v248, v8, v248
	v_add_u32_e32 v249, 0x80000, v248
	v_lshl_add_u32 v246, v5, 4, v246
	v_add_u32_e32 v247, 0x80000, v246
	s_lshl_b32 s5, s3, 21
	s_add_i32 s5, s5, s8
	s_add_i32 s5, s5, 0xc400000
	s_lshl_b32 s8, s4, 18
	s_add_i32 s5, s5, s8
	v_lshlrev_b32_e32 v8, 1, v5
	v_sub_u32_e32 v8, v4, v8
	v_and_b32_e32 v8, 15, v8
	v_lshlrev_b32_e32 v8, 4, v8
	v_lshl_add_u32 v164, v5, 13, v8
	v_add_u32_e32 v164, s5, v164
	v_xor_b32_e32 v165, 0x80, v164
	s_lshl_b32 s10, s4, 13
	s_mov_b32 s9, 0
	s_and_b32 s2, s9, 3
	s_lshl_b32 s2, s2, 8
	s_lshr_b32 s3, s9, 2
	s_lshl_b32 s3, s3, 12
	s_add_i32 s2, s2, s3
	s_add_u32 s0, s92, s2
	s_addc_u32 s1, s93, 0
	s_add_i32 s9, s9, 1
	s_mov_b32 m0, s10
	s_nop 0
	global_load_lds_dwordx4 v164, s[0:1]
	s_add_u32 s0, s0, 0x8000
	s_addc_u32 s1, s1, 0
	s_add_i32 m0, s10, 0x400
	s_nop 0
	global_load_lds_dwordx4 v165, s[0:1]
	s_add_u32 s0, s0, 0x8000
	s_addc_u32 s1, s1, 0
	s_add_i32 m0, s10, 0x800
	s_nop 0
	global_load_lds_dwordx4 v164, s[0:1]
	s_add_u32 s0, s0, 0x8000
	s_addc_u32 s1, s1, 0
	s_add_i32 m0, s10, 0xc00
	s_nop 0
	global_load_lds_dwordx4 v165, s[0:1]
	s_add_u32 s0, s0, 0x8000
	s_addc_u32 s1, s1, 0
	s_add_i32 m0, s10, 0x1000
	s_nop 0
	global_load_lds_dwordx4 v164, s[0:1]
	s_add_u32 s0, s0, 0x8000
	s_addc_u32 s1, s1, 0
	s_add_i32 m0, s10, 0x1400
	s_nop 0
	global_load_lds_dwordx4 v165, s[0:1]
	s_add_u32 s0, s0, 0x8000
	s_addc_u32 s1, s1, 0
	s_add_i32 m0, s10, 0x1800
	s_nop 0
	global_load_lds_dwordx4 v164, s[0:1]
	s_add_u32 s0, s0, 0x8000
	s_addc_u32 s1, s1, 0
	s_add_i32 m0, s10, 0x1c00
	s_nop 0
	global_load_lds_dwordx4 v165, s[0:1]
	s_xor_b32 s10, s10, 0x10000
	global_load_dwordx4 v[132:135], v246, s[92:93] offset:0
	global_load_dwordx4 v[136:139], v246, s[92:93] offset:64
	global_load_dwordx4 v[148:151], v247, s[92:93] offset:0
	global_load_dwordx4 v[152:155], v247, s[92:93] offset:64
	global_load_dwordx4 v[140:143], v246, s[92:93] offset:128
	global_load_dwordx4 v[144:147], v246, s[92:93] offset:192
	global_load_dwordx4 v[156:159], v247, s[92:93] offset:128
	global_load_dwordx4 v[160:163], v247, s[92:93] offset:192
	v_mov_b32_e32 v4, 0
	v_mov_b32_e32 v5, 0
	v_mov_b32_e32 v6, 0
	v_mov_b32_e32 v7, 0
	v_mov_b32_e32 v8, 0
	v_mov_b32_e32 v9, 0
	v_mov_b32_e32 v10, 0
	v_mov_b32_e32 v11, 0
	v_mov_b32_e32 v12, 0
	v_mov_b32_e32 v13, 0
	v_mov_b32_e32 v14, 0
	v_mov_b32_e32 v15, 0
	v_mov_b32_e32 v16, 0
	v_mov_b32_e32 v17, 0
	v_mov_b32_e32 v18, 0
	v_mov_b32_e32 v19, 0
	v_mov_b32_e32 v20, 0
	v_mov_b32_e32 v21, 0
	v_mov_b32_e32 v22, 0
	v_mov_b32_e32 v23, 0
	v_mov_b32_e32 v24, 0
	v_mov_b32_e32 v25, 0
	v_mov_b32_e32 v26, 0
	v_mov_b32_e32 v27, 0
	v_mov_b32_e32 v28, 0
	v_mov_b32_e32 v29, 0
	v_mov_b32_e32 v30, 0
	v_mov_b32_e32 v31, 0
	v_mov_b32_e32 v32, 0
	v_mov_b32_e32 v33, 0
	v_mov_b32_e32 v34, 0
	v_mov_b32_e32 v35, 0
	v_mov_b32_e32 v36, 0
	v_mov_b32_e32 v37, 0
	v_mov_b32_e32 v38, 0
	v_mov_b32_e32 v39, 0
	v_mov_b32_e32 v40, 0
	v_mov_b32_e32 v41, 0
	v_mov_b32_e32 v42, 0
	v_mov_b32_e32 v43, 0
	v_mov_b32_e32 v44, 0
	v_mov_b32_e32 v45, 0
	v_mov_b32_e32 v46, 0
	v_mov_b32_e32 v47, 0
	v_mov_b32_e32 v48, 0
	v_mov_b32_e32 v49, 0
	v_mov_b32_e32 v50, 0
	v_mov_b32_e32 v51, 0
	v_mov_b32_e32 v52, 0
	v_mov_b32_e32 v53, 0
	v_mov_b32_e32 v54, 0
	v_mov_b32_e32 v55, 0
	v_mov_b32_e32 v56, 0
	v_mov_b32_e32 v57, 0
	v_mov_b32_e32 v58, 0
	v_mov_b32_e32 v59, 0
	v_mov_b32_e32 v60, 0
	v_mov_b32_e32 v61, 0
	v_mov_b32_e32 v62, 0
	v_mov_b32_e32 v63, 0
	v_mov_b32_e32 v64, 0
	v_mov_b32_e32 v65, 0
	v_mov_b32_e32 v66, 0
	v_mov_b32_e32 v67, 0
	v_mov_b32_e32 v68, 0
	v_mov_b32_e32 v69, 0
	v_mov_b32_e32 v70, 0
	v_mov_b32_e32 v71, 0
	v_mov_b32_e32 v72, 0
	v_mov_b32_e32 v73, 0
	v_mov_b32_e32 v74, 0
	v_mov_b32_e32 v75, 0
	v_mov_b32_e32 v76, 0
	v_mov_b32_e32 v77, 0
	v_mov_b32_e32 v78, 0
	v_mov_b32_e32 v79, 0
	v_mov_b32_e32 v80, 0
	v_mov_b32_e32 v81, 0
	v_mov_b32_e32 v82, 0
	v_mov_b32_e32 v83, 0
	v_mov_b32_e32 v84, 0
	v_mov_b32_e32 v85, 0
	v_mov_b32_e32 v86, 0
	v_mov_b32_e32 v87, 0
	v_mov_b32_e32 v88, 0
	v_mov_b32_e32 v89, 0
	v_mov_b32_e32 v90, 0
	v_mov_b32_e32 v91, 0
	v_mov_b32_e32 v92, 0
	v_mov_b32_e32 v93, 0
	v_mov_b32_e32 v94, 0
	v_mov_b32_e32 v95, 0
	v_mov_b32_e32 v96, 0
	v_mov_b32_e32 v97, 0
	v_mov_b32_e32 v98, 0
	v_mov_b32_e32 v99, 0
	v_mov_b32_e32 v100, 0
	v_mov_b32_e32 v101, 0
	v_mov_b32_e32 v102, 0
	v_mov_b32_e32 v103, 0
	v_mov_b32_e32 v104, 0
	v_mov_b32_e32 v105, 0
	v_mov_b32_e32 v106, 0
	v_mov_b32_e32 v107, 0
	v_mov_b32_e32 v108, 0
	v_mov_b32_e32 v109, 0
	v_mov_b32_e32 v110, 0
	v_mov_b32_e32 v111, 0
	v_mov_b32_e32 v112, 0
	v_mov_b32_e32 v113, 0
	v_mov_b32_e32 v114, 0
	v_mov_b32_e32 v115, 0
	v_mov_b32_e32 v116, 0
	v_mov_b32_e32 v117, 0
	v_mov_b32_e32 v118, 0
	v_mov_b32_e32 v119, 0
	v_mov_b32_e32 v120, 0
	v_mov_b32_e32 v121, 0
	v_mov_b32_e32 v122, 0
	v_mov_b32_e32 v123, 0
	v_mov_b32_e32 v124, 0
	v_mov_b32_e32 v125, 0
	v_mov_b32_e32 v126, 0
	v_mov_b32_e32 v127, 0
	v_mov_b32_e32 v128, 0
	v_mov_b32_e32 v129, 0
	v_mov_b32_e32 v130, 0
	v_mov_b32_e32 v131, 0
	s_mov_b32 s4, 0

; #define LAS __attribute__((address_space(3)))
; __device__ __forceinline__ f32x4 mfma16(bf16x8 a, bf16x8 b, f32x4 c) { return __builtin_amdgcn_mfma_f32_16x16x32_bf16(a, b, c, 0, 0, 0); }
; #define LDS_BARRIER() do { asm volatile("s_waitcnt lgkmcnt(0)" ::: "memory"); __builtin_amdgcn_s_barrier(); asm volatile("" ::: "memory"); } while (0)
; #define XLOAD(kvbase, c8) do { const bf16_t* _src = (kvbase) + (((c8) >= 4) ? 2048 : 0) + ((c8) & 3) * 128 + piece * 8; \
;         _Pragma("unroll") for (int _it = 0; _it < 8; ++_it) pre[_it] = *(const u32x4*)(_src + (size_t)(srow + 32 * _it) * 4096); } while (0)
; #define XSTORE(buf) do { _Pragma("unroll") for (int _it = 0; _it < 8; ++_it) *(LAS u32x4*)((buf) + (srow + 32 * _it) * KV_STRIDE + piece * 16) = pre[_it]; } while (0)
; __device__ void cross_items(const Params& p, LAS unsigned char* lds) {
;     ...
;         for (int c = 0; c < 4; ++c) {
;             LAS unsigned char* buf = lds + (c & 1) * KV_BUF;
;             XSTORE(buf);
;             if (c < 3) XLOAD(kvb, 5 + c); else XLOAD(nkvb, 0);
;             LDS_BARRIER();
;             f32x4 ot[8];
; #pragma unroll
;             for (int c8 = 0; c8 < 8; ++c8) ot[c8] = (f32x4){0.f, 0.f, 0.f, 0.f};
;             const unsigned bb = lbase + (unsigned)((c & 1) * KV_BUF);
; #pragma unroll
;             for (int sx = 0; sx < 8; ++sx) {
;                 const unsigned aA = bb + (unsigned)((32 * sx + 4 * g + (idx >> 2)) * KV_STRIDE + 8 * (idx & 3));
;                 const unsigned aB = aA + 16u * KV_STRIDE;
;                 bf16x8 vf[4];
;                 tr_frag4(aA, aB, vf);
; #pragma unroll
;                 for (int c8 = 0; c8 < 4; ++c8) ot[c8] = mfma16(vf[c8], pf[sx], ot[c8]);
;                 tr_frag4(aA + 128, aB + 128, vf);
; #pragma unroll
;                 for (int c8 = 0; c8 < 4; ++c8) ot[4 + c8] = mfma16(vf[c8], pf[sx], ot[4 + c8]);
.Lxa_pv:
	s_waitcnt vmcnt(8)
	s_barrier
	s_and_b32 s2, s9, 3
	s_lshl_b32 s2, s2, 8
	s_lshr_b32 s3, s9, 2
	s_lshl_b32 s3, s3, 12
	s_add_i32 s2, s2, s3
	s_add_u32 s0, s92, s2
	s_addc_u32 s1, s93, 0
	s_add_i32 s9, s9, 1
	s_mov_b32 m0, s10
	s_nop 0
	global_load_lds_dwordx4 v164, s[0:1]
	s_add_u32 s0, s0, 0x8000
	s_addc_u32 s1, s1, 0
	s_add_i32 m0, s10, 0x400
	s_nop 0
	global_load_lds_dwordx4 v165, s[0:1]
	s_add_u32 s0, s0, 0x8000
	s_addc_u32 s1, s1, 0
	s_add_i32 m0, s10, 0x800
	s_nop 0
	global_load_lds_dwordx4 v164, s[0:1]
	s_add_u32 s0, s0, 0x8000
	s_addc_u32 s1, s1, 0
	s_add_i32 m0, s10, 0xc00
	s_nop 0
	global_load_lds_dwordx4 v165, s[0:1]
	s_add_u32 s0, s0, 0x8000
	s_addc_u32 s1, s1, 0
	s_add_i32 m0, s10, 0x1000
	s_nop 0
	global_load_lds_dwordx4 v164, s[0:1]
	s_add_u32 s0, s0, 0x8000
	s_addc_u32 s1, s1, 0
	s_add_i32 m0, s10, 0x1400
	s_nop 0
	global_load_lds_dwordx4 v165, s[0:1]
	s_add_u32 s0, s0, 0x8000
	s_addc_u32 s1, s1, 0
	s_add_i32 m0, s10, 0x1800
	s_nop 0
	global_load_lds_dwordx4 v164, s[0:1]
	s_add_u32 s0, s0, 0x8000
	s_addc_u32 s1, s1, 0
	s_add_i32 m0, s10, 0x1c00
	s_nop 0
	global_load_lds_dwordx4 v165, s[0:1]
	s_xor_b32 s10, s10, 0x10000
	ds_read_b64_tr_b16 v[72:73], v196
	ds_read_b64_tr_b16 v[80:81], v197
	ds_read_b64_tr_b16 v[74:75], v196 offset:4096
	ds_read_b64_tr_b16 v[82:83], v197 offset:4096
	ds_read_b64_tr_b16 v[88:89], v198
	ds_read_b64_tr_b16 v[96:97], v199
	ds_read_b64_tr_b16 v[90:91], v198 offset:4096
	ds_read_b64_tr_b16 v[98:99], v199 offset:4096
	ds_read_b64_tr_b16 v[104:105], v200
	ds_read_b64_tr_b16 v[112:113], v201
	ds_read_b64_tr_b16 v[106:107], v200 offset:4096
	ds_read_b64_tr_b16 v[114:115], v201 offset:4096
	s_waitcnt lgkmcnt(8)
	ds_read_b64_tr_b16 v[120:121], v202
	ds_read_b64_tr_b16 v[128:129], v203
	ds_read_b64_tr_b16 v[122:123], v202 offset:4096
	ds_read_b64_tr_b16 v[130:131], v203 offset:4096
	v_mfma_f32_16x16x32_bf16 v[132:135], v[72:75], v[4:7], 0
	v_mfma_f32_16x16x32_bf16 v[8:11], v[72:75], v[68:71], 0
	v_mfma_f32_16x16x32_bf16 v[136:139], v[80:83], v[4:7], 0
	v_mfma_f32_16x16x32_bf16 v[16:19], v[80:83], v[68:71], 0
	s_waitcnt lgkmcnt(8)
	ds_read_b64_tr_b16 v[72:73], v196 offset:8192
	ds_read_b64_tr_b16 v[80:81], v197 offset:8192
	ds_read_b64_tr_b16 v[74:75], v196 offset:12288
	ds_read_b64_tr_b16 v[82:83], v197 offset:12288
	v_mfma_f32_16x16x32_bf16 v[140:143], v[88:91], v[4:7], 0
	v_mfma_f32_16x16x32_bf16 v[24:27], v[88:91], v[68:71], 0
	v_mfma_f32_16x16x32_bf16 v[144:147], v[96:99], v[4:7], 0
	v_mfma_f32_16x16x32_bf16 v[32:35], v[96:99], v[68:71], 0
	s_waitcnt lgkmcnt(8)
	ds_read_b64_tr_b16 v[88:89], v198 offset:8192
	ds_read_b64_tr_b16 v[96:97], v199 offset:8192
	ds_read_b64_tr_b16 v[90:91], v198 offset:12288
	ds_read_b64_tr_b16 v[98:99], v199 offset:12288
	v_mfma_f32_16x16x32_bf16 v[148:151], v[104:107], v[4:7], 0
	v_mfma_f32_16x16x32_bf16 v[40:43], v[104:107], v[68:71], 0
	v_mfma_f32_16x16x32_bf16 v[152:155], v[112:115], v[4:7], 0
	v_mfma_f32_16x16x32_bf16 v[48:51], v[112:115], v[68:71], 0
	s_waitcnt lgkmcnt(8)
	ds_read_b64_tr_b16 v[104:105], v200 offset:8192
	ds_read_b64_tr_b16 v[112:113], v201 offset:8192
	ds_read_b64_tr_b16 v[106:107], v200 offset:12288
	ds_read_b64_tr_b16 v[114:115], v201 offset:12288
	v_mfma_f32_16x16x32_bf16 v[156:159], v[120:123], v[4:7], 0
	v_mfma_f32_16x16x32_bf16 v[56:59], v[120:123], v[68:71], 0
	v_mfma_f32_16x16x32_bf16 v[160:163], v[128:131], v[4:7], 0
	v_mfma_f32_16x16x32_bf16 v[64:67], v[128:131], v[68:71], 0
	s_waitcnt lgkmcnt(8)
	ds_read_b64_tr_b16 v[120:121], v202 offset:8192
	ds_read_b64_tr_b16 v[128:129], v203 offset:8192
	ds_read_b64_tr_b16 v[122:123], v202 offset:12288
	ds_read_b64_tr_b16 v[130:131], v203 offset:12288
	v_mfma_f32_16x16x32_bf16 v[132:135], v[72:75], v[12:15], v[132:135]
	v_mfma_f32_16x16x32_bf16 v[8:11], v[72:75], v[76:79], v[8:11]
	v_mfma_f32_16x16x32_bf16 v[136:139], v[80:83], v[12:15], v[136:139]
	v_mfma_f32_16x16x32_bf16 v[16:19], v[80:83], v[76:79], v[16:19]
	s_waitcnt lgkmcnt(8)
	ds_read_b64_tr_b16 v[72:73], v196 offset:16384
	ds_read_b64_tr_b16 v[80:81], v197 offset:16384
	ds_read_b64_tr_b16 v[74:75], v196 offset:20480
	ds_read_b64_tr_b16 v[82:83], v197 offset:20480
	v_mfma_f32_16x16x32_bf16 v[140:143], v[88:91], v[12:15], v[140:143]
	v_mfma_f32_16x16x32_bf16 v[24:27], v[88:91], v[76:79], v[24:27]
	v_mfma_f32_16x16x32_bf16 v[144:147], v[96:99], v[12:15], v[144:147]
	v_mfma_f32_16x16x32_bf16 v[32:35], v[96:99], v[76:79], v[32:35]
	s_waitcnt lgkmcnt(8)
	ds_read_b64_tr_b16 v[88:89], v198 offset:16384
	ds_read_b64_tr_b16 v[96:97], v199 offset:16384
	ds_read_b64_tr_b16 v[90:91], v198 offset:20480
	ds_read_b64_tr_b16 v[98:99], v199 offset:20480
	v_mfma_f32_16x16x32_bf16 v[148:151], v[104:107], v[12:15], v[148:151]
	v_mfma_f32_16x16x32_bf16 v[40:43], v[104:107], v[76:79], v[40:43]
	v_mfma_f32_16x16x32_bf16 v[152:155], v[112:115], v[12:15], v[152:155]
	v_mfma_f32_16x16x32_bf16 v[48:51], v[112:115], v[76:79], v[48:51]
	s_waitcnt lgkmcnt(8)
	ds_read_b64_tr_b16 v[104:105], v200 offset:16384
	ds_read_b64_tr_b16 v[112:113], v201 offset:16384
	ds_read_b64_tr_b16 v[106:107], v200 offset:20480
	ds_read_b64_tr_b16 v[114:115], v201 offset:20480
	v_mfma_f32_16x16x32_bf16 v[156:159], v[120:123], v[12:15], v[156:159]
	v_mfma_f32_16x16x32_bf16 v[56:59], v[120:123], v[76:79], v[56:59]
	v_mfma_f32_16x16x32_bf16 v[160:163], v[128:131], v[12:15], v[160:163]
	v_mfma_f32_16x16x32_bf16 v[64:67], v[128:131], v[76:79], v[64:67]
	s_waitcnt lgkmcnt(8)
; __device__ __forceinline__ f32x4 mfma16(bf16x8 a, bf16x8 b, f32x4 c) { return __builtin_amdgcn_mfma_f32_16x16x32_bf16(a, b, c, 0, 0, 0); }
; __device__ void cross_items(const Params& p, LAS unsigned char* lds) {
;     ...
; #pragma unroll
;             for (int sx = 0; sx < 8; ++sx) {
;                 const unsigned aA = bb + (unsigned)((32 * sx + 4 * g + (idx >> 2)) * KV_STRIDE + 8 * (idx & 3));
;                 const unsigned aB = aA + 16u * KV_STRIDE;
;                 bf16x8 vf[4];
;                 tr_frag4(aA, aB, vf);
; #pragma unroll
;                 for (int c8 = 0; c8 < 4; ++c8) ot[c8] = mfma16(vf[c8], pf[sx], ot[c8]);
;                 tr_frag4(aA + 128, aB + 128, vf);
; #pragma unroll
;                 for (int c8 = 0; c8 < 4; ++c8) ot[4 + c8] = mfma16(vf[c8], pf[sx], ot[4 + c8]);
	ds_read_b64_tr_b16 v[120:121], v202 offset:16384
	ds_read_b64_tr_b16 v[128:129], v203 offset:16384
	ds_read_b64_tr_b16 v[122:123], v202 offset:20480
	ds_read_b64_tr_b16 v[130:131], v203 offset:20480
	v_mfma_f32_16x16x32_bf16 v[132:135], v[72:75], v[20:23], v[132:135]
	v_mfma_f32_16x16x32_bf16 v[8:11], v[72:75], v[84:87], v[8:11]
	v_mfma_f32_16x16x32_bf16 v[136:139], v[80:83], v[20:23], v[136:139]
	v_mfma_f32_16x16x32_bf16 v[16:19], v[80:83], v[84:87], v[16:19]
	s_waitcnt lgkmcnt(8)
	ds_read_b64_tr_b16 v[72:73], v196 offset:24576
	ds_read_b64_tr_b16 v[80:81], v197 offset:24576
	ds_read_b64_tr_b16 v[74:75], v196 offset:28672
	ds_read_b64_tr_b16 v[82:83], v197 offset:28672
	v_mfma_f32_16x16x32_bf16 v[140:143], v[88:91], v[20:23], v[140:143]
	v_mfma_f32_16x16x32_bf16 v[24:27], v[88:91], v[84:87], v[24:27]
	v_mfma_f32_16x16x32_bf16 v[144:147], v[96:99], v[20:23], v[144:147]
	v_mfma_f32_16x16x32_bf16 v[32:35], v[96:99], v[84:87], v[32:35]
	s_waitcnt lgkmcnt(8)
	ds_read_b64_tr_b16 v[88:89], v198 offset:24576
	ds_read_b64_tr_b16 v[96:97], v199 offset:24576
	ds_read_b64_tr_b16 v[90:91], v198 offset:28672
	ds_read_b64_tr_b16 v[98:99], v199 offset:28672
	v_mfma_f32_16x16x32_bf16 v[148:151], v[104:107], v[20:23], v[148:151]
	v_mfma_f32_16x16x32_bf16 v[40:43], v[104:107], v[84:87], v[40:43]
	v_mfma_f32_16x16x32_bf16 v[152:155], v[112:115], v[20:23], v[152:155]
	v_mfma_f32_16x16x32_bf16 v[48:51], v[112:115], v[84:87], v[48:51]
	s_waitcnt lgkmcnt(8)
	ds_read_b64_tr_b16 v[104:105], v200 offset:24576
	ds_read_b64_tr_b16 v[112:113], v201 offset:24576
	ds_read_b64_tr_b16 v[106:107], v200 offset:28672
	ds_read_b64_tr_b16 v[114:115], v201 offset:28672
	v_mfma_f32_16x16x32_bf16 v[156:159], v[120:123], v[20:23], v[156:159]
	v_mfma_f32_16x16x32_bf16 v[56:59], v[120:123], v[84:87], v[56:59]
	v_mfma_f32_16x16x32_bf16 v[160:163], v[128:131], v[20:23], v[160:163]
	v_mfma_f32_16x16x32_bf16 v[64:67], v[128:131], v[84:87], v[64:67]
	s_waitcnt lgkmcnt(8)
	ds_read_b64_tr_b16 v[120:121], v202 offset:24576
	ds_read_b64_tr_b16 v[128:129], v203 offset:24576
	ds_read_b64_tr_b16 v[122:123], v202 offset:28672
	ds_read_b64_tr_b16 v[130:131], v203 offset:28672
	v_mfma_f32_16x16x32_bf16 v[132:135], v[72:75], v[28:31], v[132:135]
	v_mfma_f32_16x16x32_bf16 v[8:11], v[72:75], v[92:95], v[8:11]
	v_mfma_f32_16x16x32_bf16 v[136:139], v[80:83], v[28:31], v[136:139]
	v_mfma_f32_16x16x32_bf16 v[16:19], v[80:83], v[92:95], v[16:19]
	s_waitcnt lgkmcnt(8)
	ds_read_b64_tr_b16 v[72:73], v196 offset:32768
	ds_read_b64_tr_b16 v[80:81], v197 offset:32768
	ds_read_b64_tr_b16 v[74:75], v196 offset:36864
	ds_read_b64_tr_b16 v[82:83], v197 offset:36864
	v_mfma_f32_16x16x32_bf16 v[140:143], v[88:91], v[28:31], v[140:143]
	v_mfma_f32_16x16x32_bf16 v[24:27], v[88:91], v[92:95], v[24:27]
	v_mfma_f32_16x16x32_bf16 v[144:147], v[96:99], v[28:31], v[144:147]
	v_mfma_f32_16x16x32_bf16 v[32:35], v[96:99], v[92:95], v[32:35]
	s_waitcnt lgkmcnt(8)
	ds_read_b64_tr_b16 v[88:89], v198 offset:32768
	ds_read_b64_tr_b16 v[96:97], v199 offset:32768
	ds_read_b64_tr_b16 v[90:91], v198 offset:36864
	ds_read_b64_tr_b16 v[98:99], v199 offset:36864
	v_mfma_f32_16x16x32_bf16 v[148:151], v[104:107], v[28:31], v[148:151]
	v_mfma_f32_16x16x32_bf16 v[40:43], v[104:107], v[92:95], v[40:43]
	v_mfma_f32_16x16x32_bf16 v[152:155], v[112:115], v[28:31], v[152:155]
	v_mfma_f32_16x16x32_bf16 v[48:51], v[112:115], v[92:95], v[48:51]
	s_waitcnt lgkmcnt(8)
	ds_read_b64_tr_b16 v[104:105], v200 offset:32768
	ds_read_b64_tr_b16 v[112:113], v201 offset:32768
	ds_read_b64_tr_b16 v[106:107], v200 offset:36864
	ds_read_b64_tr_b16 v[114:115], v201 offset:36864
	v_mfma_f32_16x16x32_bf16 v[156:159], v[120:123], v[28:31], v[156:159]
	v_mfma_f32_16x16x32_bf16 v[56:59], v[120:123], v[92:95], v[56:59]
	v_mfma_f32_16x16x32_bf16 v[160:163], v[128:131], v[28:31], v[160:163]
	v_mfma_f32_16x16x32_bf16 v[64:67], v[128:131], v[92:95], v[64:67]
	s_waitcnt lgkmcnt(8)
	ds_read_b64_tr_b16 v[120:121], v202 offset:32768
	ds_read_b64_tr_b16 v[128:129], v203 offset:32768
	ds_read_b64_tr_b16 v[122:123], v202 offset:36864
	ds_read_b64_tr_b16 v[130:131], v203 offset:36864
	v_mfma_f32_16x16x32_bf16 v[132:135], v[72:75], v[36:39], v[132:135]
	v_mfma_f32_16x16x32_bf16 v[8:11], v[72:75], v[100:103], v[8:11]
	v_mfma_f32_16x16x32_bf16 v[136:139], v[80:83], v[36:39], v[136:139]
	v_mfma_f32_16x16x32_bf16 v[16:19], v[80:83], v[100:103], v[16:19]
	s_waitcnt lgkmcnt(8)
	ds_read_b64_tr_b16 v[72:73], v196 offset:40960
	ds_read_b64_tr_b16 v[80:81], v197 offset:40960
	ds_read_b64_tr_b16 v[74:75], v196 offset:45056
	ds_read_b64_tr_b16 v[82:83], v197 offset:45056
	v_mfma_f32_16x16x32_bf16 v[140:143], v[88:91], v[36:39], v[140:143]
	v_mfma_f32_16x16x32_bf16 v[24:27], v[88:91], v[100:103], v[24:27]
	v_mfma_f32_16x16x32_bf16 v[144:147], v[96:99], v[36:39], v[144:147]
	v_mfma_f32_16x16x32_bf16 v[32:35], v[96:99], v[100:103], v[32:35]
	s_waitcnt lgkmcnt(8)
	ds_read_b64_tr_b16 v[88:89], v198 offset:40960
	ds_read_b64_tr_b16 v[96:97], v199 offset:40960
	ds_read_b64_tr_b16 v[90:91], v198 offset:45056
	ds_read_b64_tr_b16 v[98:99], v199 offset:45056
	v_mfma_f32_16x16x32_bf16 v[148:151], v[104:107], v[36:39], v[148:151]
	v_mfma_f32_16x16x32_bf16 v[40:43], v[104:107], v[100:103], v[40:43]
	v_mfma_f32_16x16x32_bf16 v[152:155], v[112:115], v[36:39], v[152:155]
	v_mfma_f32_16x16x32_bf16 v[48:51], v[112:115], v[100:103], v[48:51]
	s_waitcnt lgkmcnt(8)
	ds_read_b64_tr_b16 v[104:105], v200 offset:40960
	ds_read_b64_tr_b16 v[112:113], v201 offset:40960
	ds_read_b64_tr_b16 v[106:107], v200 offset:45056
	ds_read_b64_tr_b16 v[114:115], v201 offset:45056
	v_mfma_f32_16x16x32_bf16 v[156:159], v[120:123], v[36:39], v[156:159]
	v_mfma_f32_16x16x32_bf16 v[56:59], v[120:123], v[100:103], v[56:59]
	v_mfma_f32_16x16x32_bf16 v[160:163], v[128:131], v[36:39], v[160:163]
	v_mfma_f32_16x16x32_bf16 v[64:67], v[128:131], v[100:103], v[64:67]
	s_waitcnt lgkmcnt(8)
; __device__ __forceinline__ f32x4 mfma16(bf16x8 a, bf16x8 b, f32x4 c) { return __builtin_amdgcn_mfma_f32_16x16x32_bf16(a, b, c, 0, 0, 0); }
; __device__ void cross_items(const Params& p, LAS unsigned char* lds) {
;     ...
; #pragma unroll
;             for (int sx = 0; sx < 8; ++sx) {
;                 const unsigned aA = bb + (unsigned)((32 * sx + 4 * g + (idx >> 2)) * KV_STRIDE + 8 * (idx & 3));
;                 const unsigned aB = aA + 16u * KV_STRIDE;
;                 bf16x8 vf[4];
;                 tr_frag4(aA, aB, vf);
; #pragma unroll
;                 for (int c8 = 0; c8 < 4; ++c8) ot[c8] = mfma16(vf[c8], pf[sx], ot[c8]);
;                 tr_frag4(aA + 128, aB + 128, vf);
; #pragma unroll
;                 for (int c8 = 0; c8 < 4; ++c8) ot[4 + c8] = mfma16(vf[c8], pf[sx], ot[4 + c8]);
	ds_read_b64_tr_b16 v[120:121], v202 offset:40960
	ds_read_b64_tr_b16 v[128:129], v203 offset:40960
	ds_read_b64_tr_b16 v[122:123], v202 offset:45056
	ds_read_b64_tr_b16 v[130:131], v203 offset:45056
	v_mfma_f32_16x16x32_bf16 v[132:135], v[72:75], v[44:47], v[132:135]
	v_mfma_f32_16x16x32_bf16 v[8:11], v[72:75], v[108:111], v[8:11]
	v_mfma_f32_16x16x32_bf16 v[136:139], v[80:83], v[44:47], v[136:139]
	v_mfma_f32_16x16x32_bf16 v[16:19], v[80:83], v[108:111], v[16:19]
	s_waitcnt lgkmcnt(8)
	ds_read_b64_tr_b16 v[72:73], v196 offset:49152
	ds_read_b64_tr_b16 v[80:81], v197 offset:49152
	ds_read_b64_tr_b16 v[74:75], v196 offset:53248
	ds_read_b64_tr_b16 v[82:83], v197 offset:53248
	v_mfma_f32_16x16x32_bf16 v[140:143], v[88:91], v[44:47], v[140:143]
	v_mfma_f32_16x16x32_bf16 v[24:27], v[88:91], v[108:111], v[24:27]
	v_mfma_f32_16x16x32_bf16 v[144:147], v[96:99], v[44:47], v[144:147]
	v_mfma_f32_16x16x32_bf16 v[32:35], v[96:99], v[108:111], v[32:35]
	s_waitcnt lgkmcnt(8)
	ds_read_b64_tr_b16 v[88:89], v198 offset:49152
	ds_read_b64_tr_b16 v[96:97], v199 offset:49152
	ds_read_b64_tr_b16 v[90:91], v198 offset:53248
	ds_read_b64_tr_b16 v[98:99], v199 offset:53248
	v_mfma_f32_16x16x32_bf16 v[148:151], v[104:107], v[44:47], v[148:151]
	v_mfma_f32_16x16x32_bf16 v[40:43], v[104:107], v[108:111], v[40:43]
	v_mfma_f32_16x16x32_bf16 v[152:155], v[112:115], v[44:47], v[152:155]
	v_mfma_f32_16x16x32_bf16 v[48:51], v[112:115], v[108:111], v[48:51]
	s_waitcnt lgkmcnt(8)
	ds_read_b64_tr_b16 v[104:105], v200 offset:49152
	ds_read_b64_tr_b16 v[112:113], v201 offset:49152
	ds_read_b64_tr_b16 v[106:107], v200 offset:53248
	ds_read_b64_tr_b16 v[114:115], v201 offset:53248
	v_mfma_f32_16x16x32_bf16 v[156:159], v[120:123], v[44:47], v[156:159]
	v_mfma_f32_16x16x32_bf16 v[56:59], v[120:123], v[108:111], v[56:59]
	v_mfma_f32_16x16x32_bf16 v[160:163], v[128:131], v[44:47], v[160:163]
	v_mfma_f32_16x16x32_bf16 v[64:67], v[128:131], v[108:111], v[64:67]
	s_waitcnt lgkmcnt(8)
	ds_read_b64_tr_b16 v[120:121], v202 offset:49152
	ds_read_b64_tr_b16 v[128:129], v203 offset:49152
	ds_read_b64_tr_b16 v[122:123], v202 offset:53248
	ds_read_b64_tr_b16 v[130:131], v203 offset:53248
	v_mfma_f32_16x16x32_bf16 v[132:135], v[72:75], v[52:55], v[132:135]
	v_mfma_f32_16x16x32_bf16 v[8:11], v[72:75], v[116:119], v[8:11]
	v_mfma_f32_16x16x32_bf16 v[136:139], v[80:83], v[52:55], v[136:139]
	v_mfma_f32_16x16x32_bf16 v[16:19], v[80:83], v[116:119], v[16:19]
	s_waitcnt lgkmcnt(8)
	ds_read_b64_tr_b16 v[72:73], v196 offset:57344
	ds_read_b64_tr_b16 v[80:81], v197 offset:57344
	ds_read_b64_tr_b16 v[74:75], v196 offset:61440
	ds_read_b64_tr_b16 v[82:83], v197 offset:61440
	v_mfma_f32_16x16x32_bf16 v[140:143], v[88:91], v[52:55], v[140:143]
	v_mfma_f32_16x16x32_bf16 v[24:27], v[88:91], v[116:119], v[24:27]
	v_mfma_f32_16x16x32_bf16 v[144:147], v[96:99], v[52:55], v[144:147]
	v_mfma_f32_16x16x32_bf16 v[32:35], v[96:99], v[116:119], v[32:35]
	s_waitcnt lgkmcnt(8)
	ds_read_b64_tr_b16 v[88:89], v198 offset:57344
	ds_read_b64_tr_b16 v[96:97], v199 offset:57344
	ds_read_b64_tr_b16 v[90:91], v198 offset:61440
	ds_read_b64_tr_b16 v[98:99], v199 offset:61440
	v_mfma_f32_16x16x32_bf16 v[148:151], v[104:107], v[52:55], v[148:151]
	v_mfma_f32_16x16x32_bf16 v[40:43], v[104:107], v[116:119], v[40:43]
	v_mfma_f32_16x16x32_bf16 v[152:155], v[112:115], v[52:55], v[152:155]
	v_mfma_f32_16x16x32_bf16 v[48:51], v[112:115], v[116:119], v[48:51]
	s_waitcnt lgkmcnt(8)
	ds_read_b64_tr_b16 v[104:105], v200 offset:57344
	ds_read_b64_tr_b16 v[112:113], v201 offset:57344
	ds_read_b64_tr_b16 v[106:107], v200 offset:61440
	ds_read_b64_tr_b16 v[114:115], v201 offset:61440
	v_mfma_f32_16x16x32_bf16 v[156:159], v[120:123], v[52:55], v[156:159]
	v_mfma_f32_16x16x32_bf16 v[56:59], v[120:123], v[116:119], v[56:59]
	v_mfma_f32_16x16x32_bf16 v[160:163], v[128:131], v[52:55], v[160:163]
	v_mfma_f32_16x16x32_bf16 v[64:67], v[128:131], v[116:119], v[64:67]
	s_waitcnt lgkmcnt(8)
	ds_read_b64_tr_b16 v[120:121], v202 offset:57344
	ds_read_b64_tr_b16 v[128:129], v203 offset:57344
	ds_read_b64_tr_b16 v[122:123], v202 offset:61440
	ds_read_b64_tr_b16 v[130:131], v203 offset:61440
	v_mfma_f32_16x16x32_bf16 v[132:135], v[72:75], v[60:63], v[132:135]
	v_mfma_f32_16x16x32_bf16 v[8:11], v[72:75], v[124:127], v[8:11]
	v_mfma_f32_16x16x32_bf16 v[136:139], v[80:83], v[60:63], v[136:139]
	v_mfma_f32_16x16x32_bf16 v[16:19], v[80:83], v[124:127], v[16:19]
	s_waitcnt lgkmcnt(8)
	v_mfma_f32_16x16x32_bf16 v[140:143], v[88:91], v[60:63], v[140:143]
	v_mfma_f32_16x16x32_bf16 v[24:27], v[88:91], v[124:127], v[24:27]
	v_mfma_f32_16x16x32_bf16 v[144:147], v[96:99], v[60:63], v[144:147]
	v_mfma_f32_16x16x32_bf16 v[32:35], v[96:99], v[124:127], v[32:35]
	s_waitcnt lgkmcnt(4)
	v_mfma_f32_16x16x32_bf16 v[148:151], v[104:107], v[60:63], v[148:151]
	v_mfma_f32_16x16x32_bf16 v[40:43], v[104:107], v[124:127], v[40:43]
	v_mfma_f32_16x16x32_bf16 v[152:155], v[112:115], v[60:63], v[152:155]
	v_mfma_f32_16x16x32_bf16 v[48:51], v[112:115], v[124:127], v[48:51]
	s_waitcnt lgkmcnt(0)
; __device__ __forceinline__ unsigned cvt_pk_bf16(float lo, float hi) { const f32x2v v = {lo, hi}; const b16x2v r = __builtin_convertvector(v, b16x2v); return __builtin_bit_cast(unsigned, r); }
; __device__ void cross_items(const Params& p, LAS unsigned char* lds) {
;     ...
; #pragma unroll
;             for (int c8 = 0; c8 < 8; ++c8) { u32x2 wv; wv.x = cvt_pk_bf16(ot[c8][0] * inv, ot[c8][1] * inv); wv.y = cvt_pk_bf16(ot[c8][2] * inv, ot[c8][3] * inv);
;                 *(u32x2*)(oc + tok * DM + head * 512 + c * 128 + 16 * c8 + 4 * g) = wv; }
;         }
	v_mfma_f32_16x16x32_bf16 v[156:159], v[120:123], v[60:63], v[156:159]
	v_mfma_f32_16x16x32_bf16 v[56:59], v[120:123], v[124:127], v[56:59]
	v_mfma_f32_16x16x32_bf16 v[160:163], v[128:131], v[60:63], v[160:163]
	v_mfma_f32_16x16x32_bf16 v[64:67], v[128:131], v[124:127], v[64:67]
	s_nop 7
	s_nop 7
	v_mul_f32_e32 v132, v244, v132
	v_mul_f32_e32 v133, v244, v133
	v_mul_f32_e32 v134, v244, v134
	v_mul_f32_e32 v135, v244, v135
	v_mul_f32_e32 v136, v244, v136
	v_mul_f32_e32 v137, v244, v137
	v_mul_f32_e32 v138, v244, v138
	v_mul_f32_e32 v139, v244, v139
	v_cvt_pk_bf16_f32 v230, v132, v133
	v_cvt_pk_bf16_f32 v231, v134, v135
	v_cvt_pk_bf16_f32 v232, v136, v137
	v_cvt_pk_bf16_f32 v233, v138, v139
	s_nop 1
	v_permlane16_swap_b32 v230, v232
	v_permlane16_swap_b32 v231, v233
	global_store_dwordx4 v248, v[230:233], s[92:93]
	v_mul_f32_e32 v140, v244, v140
	v_mul_f32_e32 v141, v244, v141
	v_mul_f32_e32 v142, v244, v142
	v_mul_f32_e32 v143, v244, v143
	v_mul_f32_e32 v144, v244, v144
	v_mul_f32_e32 v145, v244, v145
	v_mul_f32_e32 v146, v244, v146
	v_mul_f32_e32 v147, v244, v147
	v_cvt_pk_bf16_f32 v234, v140, v141
	v_cvt_pk_bf16_f32 v235, v142, v143
	v_cvt_pk_bf16_f32 v236, v144, v145
	v_cvt_pk_bf16_f32 v237, v146, v147
	s_nop 1
	v_permlane16_swap_b32 v234, v236
	v_permlane16_swap_b32 v235, v237
	global_store_dwordx4 v248, v[234:237], s[92:93] offset:64
	v_mul_f32_e32 v148, v244, v148
	v_mul_f32_e32 v149, v244, v149
	v_mul_f32_e32 v150, v244, v150
	v_mul_f32_e32 v151, v244, v151
	v_mul_f32_e32 v152, v244, v152
	v_mul_f32_e32 v153, v244, v153
	v_mul_f32_e32 v154, v244, v154
	v_mul_f32_e32 v155, v244, v155
	v_cvt_pk_bf16_f32 v230, v148, v149
	v_cvt_pk_bf16_f32 v231, v150, v151
	v_cvt_pk_bf16_f32 v232, v152, v153
	v_cvt_pk_bf16_f32 v233, v154, v155
	s_nop 1
	v_permlane16_swap_b32 v230, v232
	v_permlane16_swap_b32 v231, v233
	global_store_dwordx4 v248, v[230:233], s[92:93] offset:128
	v_mul_f32_e32 v156, v244, v156
	v_mul_f32_e32 v157, v244, v157
	v_mul_f32_e32 v158, v244, v158
	v_mul_f32_e32 v159, v244, v159
	v_mul_f32_e32 v160, v244, v160
	v_mul_f32_e32 v161, v244, v161
	v_mul_f32_e32 v162, v244, v162
	v_mul_f32_e32 v163, v244, v163
	v_cvt_pk_bf16_f32 v234, v156, v157
	v_cvt_pk_bf16_f32 v235, v158, v159
	v_cvt_pk_bf16_f32 v236, v160, v161
	v_cvt_pk_bf16_f32 v237, v162, v163
	s_nop 1
	v_permlane16_swap_b32 v234, v236
	v_permlane16_swap_b32 v235, v237
	global_store_dwordx4 v248, v[234:237], s[92:93] offset:192
	v_add_u32_e32 v248, 0x100, v248
	v_mul_f32_e32 v8, v245, v8
	v_mul_f32_e32 v9, v245, v9
	v_mul_f32_e32 v10, v245, v10
	v_mul_f32_e32 v11, v245, v11
	v_mul_f32_e32 v16, v245, v16
	v_mul_f32_e32 v17, v245, v17
	v_mul_f32_e32 v18, v245, v18
	v_mul_f32_e32 v19, v245, v19
	v_cvt_pk_bf16_f32 v230, v8, v9
	v_cvt_pk_bf16_f32 v231, v10, v11
	v_cvt_pk_bf16_f32 v232, v16, v17
	v_cvt_pk_bf16_f32 v233, v18, v19
	s_nop 1
	v_permlane16_swap_b32 v230, v232
	v_permlane16_swap_b32 v231, v233
	global_store_dwordx4 v249, v[230:233], s[92:93]
	v_mul_f32_e32 v24, v245, v24
	v_mul_f32_e32 v25, v245, v25
	v_mul_f32_e32 v26, v245, v26
	v_mul_f32_e32 v27, v245, v27
	v_mul_f32_e32 v32, v245, v32
	v_mul_f32_e32 v33, v245, v33
	v_mul_f32_e32 v34, v245, v34
	v_mul_f32_e32 v35, v245, v35
	v_cvt_pk_bf16_f32 v234, v24, v25
	v_cvt_pk_bf16_f32 v235, v26, v27
	v_cvt_pk_bf16_f32 v236, v32, v33
	v_cvt_pk_bf16_f32 v237, v34, v35
	s_nop 1
	v_permlane16_swap_b32 v234, v236
	v_permlane16_swap_b32 v235, v237
	global_store_dwordx4 v249, v[234:237], s[92:93] offset:64
	v_mul_f32_e32 v40, v245, v40
	v_mul_f32_e32 v41, v245, v41
	v_mul_f32_e32 v42, v245, v42
	v_mul_f32_e32 v43, v245, v43
	v_mul_f32_e32 v48, v245, v48
	v_mul_f32_e32 v49, v245, v49
	v_mul_f32_e32 v50, v245, v50
	v_mul_f32_e32 v51, v245, v51
	v_cvt_pk_bf16_f32 v230, v40, v41
	v_cvt_pk_bf16_f32 v231, v42, v43
	v_cvt_pk_bf16_f32 v232, v48, v49
	v_cvt_pk_bf16_f32 v233, v50, v51
	s_nop 1
	v_permlane16_swap_b32 v230, v232
	v_permlane16_swap_b32 v231, v233
	global_store_dwordx4 v249, v[230:233], s[92:93] offset:128
	v_mul_f32_e32 v56, v245, v56
	v_mul_f32_e32 v57, v245, v57
	v_mul_f32_e32 v58, v245, v58
	v_mul_f32_e32 v59, v245, v59
	v_mul_f32_e32 v64, v245, v64
	v_mul_f32_e32 v65, v245, v65
	v_mul_f32_e32 v66, v245, v66
	v_mul_f32_e32 v67, v245, v67
	v_cvt_pk_bf16_f32 v234, v56, v57
	v_cvt_pk_bf16_f32 v235, v58, v59
	v_cvt_pk_bf16_f32 v236, v64, v65
	v_cvt_pk_bf16_f32 v237, v66, v67
	s_nop 1
	v_permlane16_swap_b32 v234, v236
	v_permlane16_swap_b32 v235, v237
	global_store_dwordx4 v249, v[234:237], s[92:93] offset:192
	v_add_u32_e32 v249, 0x100, v249
	v_xor_b32_e32 v196, 0x10000, v196
	v_xor_b32_e32 v197, 0x10000, v197
	v_xor_b32_e32 v198, 0x10000, v198
	v_xor_b32_e32 v199, 0x10000, v199
	v_xor_b32_e32 v200, 0x10000, v200
	v_xor_b32_e32 v201, 0x10000, v201
	v_xor_b32_e32 v202, 0x10000, v202
	v_xor_b32_e32 v203, 0x10000, v203
	s_add_i32 s4, s4, 1
	s_cmp_lt_u32 s4, 4
	s_cbranch_scc1 .Lxa_pv
	s_waitcnt vmcnt(0)
	s_waitcnt lgkmcnt(0)
	s_barrier

; #define LAS __attribute__((address_space(3)))
; #define LDS_BARRIER() do { asm volatile("s_waitcnt lgkmcnt(0)" ::: "memory"); __builtin_amdgcn_s_barrier(); asm volatile("" ::: "memory"); } while (0)
; __global__ void __launch_bounds__(512, 2) fwd_megakernel(Params p) {
;     ...
;                         if (threadIdx.x == 0) *(LAS int*)(lds + LDS_SLOT) = (int)atomicAdd(ctr, 1u);
;                         LDS_BARRIER();
;                         const int next = *(LAS int*)(lds + LDS_SLOT);
.LBB0_432:
	s_or_b64 exec, exec, s[0:1]
	s_and_saveexec_b64 s[0:1], s[62:63]
	s_cbranch_execz .Ldil_noslot
	s_waitcnt vmcnt(4)
	v_mov_b32_e32 v161, s38
	ds_write_b32 v161, v160

; #define LAS __attribute__((address_space(3)))
; __device__ __forceinline__ int opaque_tid() { int t = (int)threadIdx.x; asm volatile("" : "+v"(t)); return t; }
; #define LDS_BARRIER() do { asm volatile("s_waitcnt lgkmcnt(0)" ::: "memory"); __builtin_amdgcn_s_barrier(); asm volatile("" ::: "memory"); } while (0)
; __device__ __forceinline__ void dilated_item(const Params& p, int item, int next, u32x4 (&pk)[8], u32x4 (&pv)[8], LAS unsigned char* lds) {
;     const int tid = opaque_tid(), lane = tid & 63, w = __builtin_amdgcn_readfirstlane(tid >> 6), idx = lane & 15, g = lane >> 4;
;     const int pat = item >> 10, rem = item & 1023, b = rem >> 8, head = (rem >> 5) & 7, sb = rem & 31;
;     const int dsh = pat * 2, nbsh = 5 - dsh;
;     const int r = sb >> nbsh, blk = sb & ((1 << nbsh) - 1);
;     unsigned char* ws = p.ws;
;     const bf16_t* hb = (const bf16_t*)(ws + OFF_H) + (size_t)(b * SEQ) * HC;
;     const unsigned lbase = (unsigned)(size_t)lds;
;     { const int piece = tid & 15;
; #pragma unroll
;       for (int it = 0; it < 8; ++it) { const int row = (tid >> 4) + 32 * it;
;           *(LAS u32x4*)(lds + row * KV_STRIDE + piece * 16) = pk[it]; *(LAS u32x4*)(lds + KV_BUF + row * KV_STRIDE + piece * 16) = pv[it]; } }
;     const int qpos = r + ((blk * 128 + 16 * w + idx) << dsh);
;     bf16x8 qf[4];
;     { const bf16_t* qp = hb + (size_t)qpos * HC + 3072 + head * 128 + 8 * g;
; #pragma unroll
;       for (int ks = 0; ks < 4; ++ks) qf[ks] = *(const bf16x8*)(qp + 32 * ks); }
;     if (next < 3072) dil_preload(p, next, tid, pk, pv);
;     LDS_BARRIER();
.LBB0_433:
	s_ashr_i32 s4, s8, 10
	s_lshl_b32 s10, s4, 1
	s_sub_i32 s0, 5, s10
	s_lshl_b32 s5, s8, 4
	s_lshl_b32 s1, -1, s0
	s_and_b32 s5, s5, 0x3000
	s_and_b32 s6, s8, 31
	v_mov_b32_e32 v84, v212
	s_bfe_u32 s9, s8, 0x30005
	s_add_i32 s11, 0, 0x11000
	s_lshr_b32 s12, s6, s0
	s_andn2_b32 s6, s6, s1
	s_mul_i32 s0, s5, 0x3000
	s_add_u32 s0, s92, s0
	v_readfirstlane_b32 s7, v84
	s_addc_u32 s1, s93, 0
	s_ashr_i32 s7, s7, 2
	s_lshl_b32 s15, s6, 7
	s_and_b32 s13, s7, -16
	v_and_b32_e32 v118, 15, v84
	s_add_i32 s7, s13, s15
	v_or_b32_e32 v0, s7, v118
	v_lshlrev_b32_e32 v0, s10, v0
	v_add_u32_e32 v117, s12, v0
	v_mov_b64_e32 v[0:1], s[0:1]
	v_bfe_u32 v116, v84, 4, 2
	v_mad_i64_i32 v[0:1], s[0:1], v117, s48, v[0:1]
	s_lshl_b32 s18, s9, 8
	v_lshl_add_u64 v[0:1], v[0:1], 0, s[18:19]
	v_lshlrev_b32_e32 v2, 4, v116
	v_lshl_add_u64 v[0:1], v[0:1], 0, v[2:3]
	s_mov_b64 s[0:1], 0xd101800
	v_lshl_add_u64 v[68:69], v[0:1], 0, s[0:1]
	v_add_co_u32_e32 v0, vcc, 0xd101000, v0
	v_ashrrev_i32_e32 v85, 4, v84
	s_nop 0
	v_addc_co_u32_e32 v1, vcc, 0, v1, vcc
	global_load_dwordx4 v[76:79], v[68:69], off offset:64
	global_load_dwordx4 v[72:75], v[68:69], off offset:128
	global_load_dwordx4 v[80:83], v[0:1], off offset:2048
	s_nop 0
	global_load_dwordx4 v[68:71], v[68:69], off offset:192
	v_lshlrev_b32_e32 v0, 4, v84
	s_movk_i32 s7, 0xbff
	v_and_b32_e32 v0, 0xf0, v0
	v_mul_lo_u32 v1, v85, s99
	s_waitcnt lgkmcnt(0)
	v_cmp_lt_i32_e64 s[36:37], s7, v86
	s_movk_i32 s7, 0xc00
	v_add3_u32 v2, 0, v0, v1
	v_add3_u32 v1, s11, v0, v1
	v_cmp_gt_i32_e32 vcc, s7, v86
	v_readfirstlane_b32 s10, v86
	s_waitcnt vmcnt(9)
	ds_write_b128 v2, v[12:15]
	ds_write_b128 v1, v[8:11]
	ds_write_b128 v2, v[16:19] offset:8704
	ds_write_b128 v1, v[4:7] offset:8704
	ds_write_b128 v2, v[28:31] offset:17408
	ds_write_b128 v1, v[24:27] offset:17408
	ds_write_b128 v2, v[32:35] offset:26112
	ds_write_b128 v1, v[20:23] offset:26112
	ds_write_b128 v2, v[44:47] offset:34816
	ds_write_b128 v1, v[40:43] offset:34816
	ds_write_b128 v2, v[48:51] offset:43520
	ds_write_b128 v1, v[36:39] offset:43520
	ds_write_b128 v2, v[60:63] offset:52224
	ds_write_b128 v1, v[56:59] offset:52224
	ds_write_b128 v2, v[64:67] offset:60928
	ds_write_b128 v1, v[52:55] offset:60928
	s_mov_b64 s[0:1], -1
	v_lshlrev_b32_e32 v2, 3, v84
	s_cbranch_vccnz .LBB0_439
	v_lshlrev_b32_e32 v1, 3, v84
	s_mov_b64 s[0:1], 0

; __device__ __forceinline__ f32x4 mfma16(bf16x8 a, bf16x8 b, f32x4 c) { return __builtin_amdgcn_mfma_f32_16x16x32_bf16(a, b, c, 0, 0, 0); }
; __device__ __forceinline__ void dilated_item(const Params& p, int item, int next, u32x4 (&pk)[8], u32x4 (&pv)[8], LAS unsigned char* lds) {
;     ...
;     f32x4 sc[9];
; #pragma unroll
;     for (int tt = 0; tt < 9; ++tt) {
;         sc[tt] = (f32x4){0.f, 0.f, 0.f, 0.f};
; #pragma unroll
;         for (int ks = 0; ks < 4; ++ks) sc[tt] = mfma16(frag_row(lds, KV_STRIDE, 16 * (w + tt), 32 * ks, idx, g), qf[ks], sc[tt]);
;     }
.Ldil_qb:
	v_mfma_f32_16x16x32_bf16 v[108:111], v[88:91], v[68:71], v[84:87]
	s_nop 3
	ds_read_b128 v[84:87], v92
	ds_read_b128 v[88:91], v92 offset:64
	v_or_b32_e32 v2, s24, v118
	s_waitcnt lgkmcnt(1)
	v_mfma_f32_16x16x32_bf16 v[84:87], v[84:87], v[80:83], 0
	s_add_i32 s16, s13, 0x70
	s_add_i32 s15, s13, 0x80
	s_lshl_b32 s12, s9, 7
	s_waitcnt lgkmcnt(0)
	v_mfma_f32_16x16x32_bf16 v[84:87], v[88:91], v[76:79], v[84:87]
	ds_read_b128 v[88:91], v92 offset:128
	s_cmp_lg_u32 s6, 0
	s_cselect_b64 s[6:7], -1, 0
	s_waitcnt lgkmcnt(0)
	v_mfma_f32_16x16x32_bf16 v[84:87], v[88:91], v[72:75], v[84:87]
	ds_read_b128 v[88:91], v92 offset:192
	v_mad_u64_u32 v[92:93], s[0:1], v2, s99, v[0:1]
	s_waitcnt lgkmcnt(0)
	v_mfma_f32_16x16x32_bf16 v[112:115], v[88:91], v[68:71], v[84:87]
	s_nop 3
	ds_read_b128 v[84:87], v92
	ds_read_b128 v[88:91], v92 offset:64
	v_or_b32_e32 v2, s23, v118
	s_waitcnt lgkmcnt(1)
	v_mfma_f32_16x16x32_bf16 v[84:87], v[84:87], v[80:83], 0
	s_waitcnt lgkmcnt(0)
	v_mfma_f32_16x16x32_bf16 v[84:87], v[88:91], v[76:79], v[84:87]
	ds_read_b128 v[88:91], v92 offset:128
	s_waitcnt lgkmcnt(0)
	v_mfma_f32_16x16x32_bf16 v[84:87], v[88:91], v[72:75], v[84:87]
	ds_read_b128 v[88:91], v92 offset:192
	v_mad_u64_u32 v[92:93], s[0:1], v2, s99, v[0:1]
	s_waitcnt lgkmcnt(0)
	v_mfma_f32_16x16x32_bf16 v[104:107], v[88:91], v[68:71], v[84:87]
	s_nop 3
	ds_read_b128 v[84:87], v92
	ds_read_b128 v[88:91], v92 offset:64
	v_or_b32_e32 v2, s22, v118
	s_waitcnt lgkmcnt(1)
	v_mfma_f32_16x16x32_bf16 v[84:87], v[84:87], v[80:83], 0
	s_waitcnt lgkmcnt(0)
	v_mfma_f32_16x16x32_bf16 v[84:87], v[88:91], v[76:79], v[84:87]
	ds_read_b128 v[88:91], v92 offset:128
	s_waitcnt lgkmcnt(0)
	v_mfma_f32_16x16x32_bf16 v[84:87], v[88:91], v[72:75], v[84:87]
	ds_read_b128 v[88:91], v92 offset:192
	v_mad_u64_u32 v[92:93], s[0:1], v2, s99, v[0:1]
	s_waitcnt lgkmcnt(0)
	v_mfma_f32_16x16x32_bf16 v[100:103], v[88:91], v[68:71], v[84:87]
	s_nop 3
	ds_read_b128 v[84:87], v92
	ds_read_b128 v[88:91], v92 offset:64
	v_or_b32_e32 v2, s18, v118
	s_waitcnt lgkmcnt(1)
	v_mfma_f32_16x16x32_bf16 v[84:87], v[84:87], v[80:83], 0
	s_waitcnt lgkmcnt(0)
	v_mfma_f32_16x16x32_bf16 v[84:87], v[88:91], v[76:79], v[84:87]
	ds_read_b128 v[88:91], v92 offset:128
	s_waitcnt lgkmcnt(0)
	v_mfma_f32_16x16x32_bf16 v[84:87], v[88:91], v[72:75], v[84:87]
	ds_read_b128 v[88:91], v92 offset:192
	v_mad_u64_u32 v[92:93], s[0:1], v2, s99, v[0:1]
	s_waitcnt lgkmcnt(0)
	v_mfma_f32_16x16x32_bf16 v[96:99], v[88:91], v[68:71], v[84:87]
	s_nop 3
	ds_read_b128 v[84:87], v92
	ds_read_b128 v[88:91], v92 offset:64
	v_or_b32_e32 v2, s17, v118
	s_waitcnt lgkmcnt(1)
	v_mfma_f32_16x16x32_bf16 v[84:87], v[84:87], v[80:83], 0
	v_mad_u64_u32 v[120:121], s[0:1], v2, s99, v[0:1]
	v_or_b32_e32 v2, s16, v118
	s_waitcnt lgkmcnt(0)
	v_mfma_f32_16x16x32_bf16 v[84:87], v[88:91], v[76:79], v[84:87]
	ds_read_b128 v[88:91], v92 offset:128
	v_mad_u64_u32 v[124:125], s[0:1], v2, s99, v[0:1]
	s_waitcnt lgkmcnt(0)
	v_mfma_f32_16x16x32_bf16 v[84:87], v[88:91], v[72:75], v[84:87]
	ds_read_b128 v[88:91], v92 offset:192
	v_or_b32_e32 v2, s15, v118
	s_waitcnt lgkmcnt(0)
	v_mfma_f32_16x16x32_bf16 v[92:95], v[88:91], v[68:71], v[84:87]
	s_nop 3
	ds_read_b128 v[84:87], v120
	ds_read_b128 v[88:91], v120 offset:64
	s_waitcnt lgkmcnt(1)
	v_mfma_f32_16x16x32_bf16 v[84:87], v[84:87], v[80:83], 0
	s_waitcnt lgkmcnt(0)
	v_mfma_f32_16x16x32_bf16 v[84:87], v[88:91], v[76:79], v[84:87]
	ds_read_b128 v[88:91], v120 offset:128
	s_waitcnt lgkmcnt(0)
	v_mfma_f32_16x16x32_bf16 v[84:87], v[88:91], v[72:75], v[84:87]
	ds_read_b128 v[88:91], v120 offset:192
	ds_read_b128 v[120:123], v124 offset:64
	s_waitcnt lgkmcnt(1)
	v_mfma_f32_16x16x32_bf16 v[88:91], v[88:91], v[68:71], v[84:87]
	s_nop 3
	ds_read_b128 v[84:87], v124
	s_nop 2
	v_mul_f32_e32 v88, 0x3fb8aa3b, v88
	s_waitcnt lgkmcnt(0)
	v_mfma_f32_16x16x32_bf16 v[84:87], v[84:87], v[80:83], 0
	v_mul_f32_e32 v89, 0x3fb8aa3b, v89
	v_mul_f32_e32 v90, 0x3fb8aa3b, v90
	v_mul_f32_e32 v91, 0x3fb8aa3b, v91
	v_mfma_f32_16x16x32_bf16 v[84:87], v[120:123], v[76:79], v[84:87]
	ds_read_b128 v[120:123], v124 offset:128
	s_waitcnt lgkmcnt(0)
	v_mfma_f32_16x16x32_bf16 v[84:87], v[120:123], v[72:75], v[84:87]
	ds_read_b128 v[120:123], v124 offset:192
	v_mad_u64_u32 v[124:125], s[0:1], v2, s99, v[0:1]
	s_waitcnt lgkmcnt(0)
	v_mfma_f32_16x16x32_bf16 v[84:87], v[120:123], v[68:71], v[84:87]
	ds_read_b128 v[120:123], v124
	v_or_b32_e32 v0, 0x80, v118
	s_nop 5
	v_mul_f32_e32 v84, 0x3fb8aa3b, v84
	s_waitcnt lgkmcnt(0)
	v_mfma_f32_16x16x32_bf16 v[80:83], v[120:123], v[80:83], 0
	ds_read_b128 v[120:123], v124 offset:64
	s_waitcnt lgkmcnt(0)
	v_mfma_f32_16x16x32_bf16 v[76:79], v[120:123], v[76:79], v[80:83]
	s_nop 4
	ds_read_b128 v[80:83], v124 offset:128
	s_waitcnt lgkmcnt(0)
	v_mfma_f32_16x16x32_bf16 v[72:75], v[80:83], v[72:75], v[76:79]
	s_nop 2
	ds_read_b128 v[76:79], v124 offset:192
	s_waitcnt lgkmcnt(0)
; __device__ __forceinline__ void dilated_item(const Params& p, int item, int next, u32x4 (&pk)[8], u32x4 (&pv)[8], LAS unsigned char* lds) {
;     ...
;     const int qi = 128 + 16 * w + idx;
;     float mx = -1e30f;
; #pragma unroll
;     for (int tt = 0; tt < 9; ++tt)
; #pragma unroll
;         for (int rr = 0; rr < 4; ++rr) {
;             const int kj = 16 * (w + tt) + 4 * g + rr, diff = qi - kj;
;             const bool valid = (diff >= 0) && (diff <= 128) && (blk > 0 || kj >= 128);
;             const float s = valid ? sc[tt][rr] * LOG2E : -1e30f;
;             sc[tt][rr] = s; mx = fmaxf(mx, s);
;         }
	v_mfma_f32_16x16x32_bf16 v[68:71], v[76:79], v[68:71], v[72:75]
	s_nop 2
	v_lshlrev_b32_e32 v72, 2, v116
	v_or_b32_e32 v2, s13, v72
	v_sub_u32_e32 v73, v0, v72
	v_cmp_lt_i32_e64 s[0:1], s33, v2
	v_cmp_gt_u32_e32 vcc, s29, v73
	s_or_b64 s[0:1], s[6:7], s[0:1]
	v_add_u32_e32 v79, s13, v0
	s_and_b64 vcc, vcc, s[0:1]
	v_mul_f32_e32 v73, 0x3fb8aa3b, v108
	v_sub_u32_e32 v0, v72, v0
	v_cmp_lt_i32_e64 s[0:1], s53, v2
	v_cndmask_b32_e32 v80, v228, v73, vcc
	v_cmp_lt_u32_e32 vcc, s28, v0
	s_or_b64 s[0:1], s[6:7], s[0:1]
	v_or_b32_e32 v73, 2, v2
	s_and_b64 vcc, vcc, s[0:1]
	v_mul_f32_e32 v0, 0x3fb8aa3b, v109
	v_sub_u32_e32 v74, v79, v73
	v_cmp_lt_i32_e64 s[0:1], s33, v73
	v_cndmask_b32_e32 v81, v228, v0, vcc
	v_cmp_gt_u32_e32 vcc, s29, v74
	s_or_b64 s[0:1], s[6:7], s[0:1]
	s_and_b64 vcc, vcc, s[0:1]
	v_mul_f32_e32 v73, 0x3fb8aa3b, v110
	v_cndmask_b32_e32 v82, v228, v73, vcc
	v_or_b32_e32 v73, 3, v2
	v_sub_u32_e32 v74, v79, v73
	v_cmp_lt_i32_e64 s[0:1], s33, v73
	v_cmp_gt_u32_e32 vcc, s29, v74
	s_or_b64 s[0:1], s[6:7], s[0:1]
	s_and_b64 vcc, vcc, s[0:1]
	v_mul_f32_e32 v73, 0x3fb8aa3b, v111
	v_or_b32_e32 v78, s25, v72
	v_cndmask_b32_e32 v83, v228, v73, vcc
	v_sub_u32_e32 v73, v79, v78
	v_cmp_lt_i32_e64 s[0:1], s33, v78
	v_cmp_gt_u32_e32 vcc, s29, v73
	s_or_b64 s[0:1], s[6:7], s[0:1]
	s_and_b64 vcc, vcc, s[0:1]
	v_mul_f32_e32 v73, 0x3fb8aa3b, v112
	v_cndmask_b32_e32 v108, v228, v73, vcc
	v_sub_u32_e32 v73, v78, v79
	v_cmp_lt_i32_e64 s[0:1], s53, v78
	v_cmp_lt_u32_e32 vcc, s28, v73
	s_or_b64 s[0:1], s[6:7], s[0:1]
	s_and_b64 vcc, vcc, s[0:1]
	v_mul_f32_e32 v73, 0x3fb8aa3b, v113
	v_cndmask_b32_e32 v109, v228, v73, vcc
	v_or_b32_e32 v73, 2, v78
	v_sub_u32_e32 v74, v79, v73
	v_cmp_lt_i32_e64 s[0:1], s33, v73
	v_cmp_gt_u32_e32 vcc, s29, v74
	s_or_b64 s[0:1], s[6:7], s[0:1]
	s_and_b64 vcc, vcc, s[0:1]
	v_mul_f32_e32 v73, 0x3fb8aa3b, v114
	v_cndmask_b32_e32 v110, v228, v73, vcc
	v_or_b32_e32 v73, 3, v78
	v_sub_u32_e32 v74, v79, v73
	v_cmp_lt_i32_e64 s[0:1], s33, v73
	v_cmp_gt_u32_e32 vcc, s29, v74
	s_or_b64 s[0:1], s[6:7], s[0:1]
	s_and_b64 vcc, vcc, s[0:1]
	v_mul_f32_e32 v73, 0x3fb8aa3b, v115
	v_or_b32_e32 v74, s24, v72
	v_cndmask_b32_e32 v111, v228, v73, vcc
	v_sub_u32_e32 v73, v79, v74
	v_cmp_lt_i32_e64 s[0:1], s33, v74
	v_cmp_gt_u32_e32 vcc, s29, v73
	s_or_b64 s[0:1], s[6:7], s[0:1]
	s_and_b64 vcc, vcc, s[0:1]
	v_mul_f32_e32 v73, 0x3fb8aa3b, v104
	v_cndmask_b32_e32 v104, v228, v73, vcc
	v_sub_u32_e32 v73, v74, v79
	v_cmp_lt_i32_e64 s[0:1], s53, v74
	v_cmp_lt_u32_e32 vcc, s28, v73
	s_or_b64 s[0:1], s[6:7], s[0:1]
	s_and_b64 vcc, vcc, s[0:1]
	v_mul_f32_e32 v73, 0x3fb8aa3b, v105
	v_cndmask_b32_e32 v105, v228, v73, vcc
	v_or_b32_e32 v73, 2, v74
	v_sub_u32_e32 v75, v79, v73
	v_cmp_lt_i32_e64 s[0:1], s33, v73
	v_cmp_gt_u32_e32 vcc, s29, v75
	s_or_b64 s[0:1], s[6:7], s[0:1]
	s_and_b64 vcc, vcc, s[0:1]
	v_mul_f32_e32 v73, 0x3fb8aa3b, v106
	v_cndmask_b32_e32 v106, v228, v73, vcc
	v_or_b32_e32 v73, 3, v74
	v_sub_u32_e32 v75, v79, v73
	v_cmp_lt_i32_e64 s[0:1], s33, v73
	v_cmp_gt_u32_e32 vcc, s29, v75
	s_or_b64 s[0:1], s[6:7], s[0:1]
	s_and_b64 vcc, vcc, s[0:1]
	v_mul_f32_e32 v73, 0x3fb8aa3b, v107
	v_or_b32_e32 v77, s23, v72
	v_cndmask_b32_e32 v107, v228, v73, vcc
	v_sub_u32_e32 v73, v79, v77
	v_cmp_lt_i32_e64 s[0:1], s33, v77
	v_cmp_gt_u32_e32 vcc, s29, v73
	s_or_b64 s[0:1], s[6:7], s[0:1]
	s_and_b64 vcc, vcc, s[0:1]
	v_mul_f32_e32 v73, 0x3fb8aa3b, v100
	v_cndmask_b32_e32 v112, v228, v73, vcc
	v_sub_u32_e32 v73, v77, v79
	v_cmp_lt_i32_e64 s[0:1], s53, v77
	v_cmp_lt_u32_e32 vcc, s28, v73
	s_or_b64 s[0:1], s[6:7], s[0:1]
	s_and_b64 vcc, vcc, s[0:1]
	v_mul_f32_e32 v73, 0x3fb8aa3b, v101
	v_cndmask_b32_e32 v113, v228, v73, vcc
	v_or_b32_e32 v73, 2, v77
	v_sub_u32_e32 v75, v79, v73
	v_cmp_lt_i32_e64 s[0:1], s33, v73
	v_cmp_gt_u32_e32 vcc, s29, v75
	s_or_b64 s[0:1], s[6:7], s[0:1]
	s_and_b64 vcc, vcc, s[0:1]
	v_mul_f32_e32 v73, 0x3fb8aa3b, v102
	v_cndmask_b32_e32 v114, v228, v73, vcc
	v_or_b32_e32 v73, 3, v77
	v_sub_u32_e32 v75, v79, v73
	v_cmp_lt_i32_e64 s[0:1], s33, v73
	v_cmp_gt_u32_e32 vcc, s29, v75
	s_or_b64 s[0:1], s[6:7], s[0:1]
	s_and_b64 vcc, vcc, s[0:1]
	v_mul_f32_e32 v73, 0x3fb8aa3b, v103
	v_cndmask_b32_e32 v115, v228, v73, vcc
	v_or_b32_e32 v73, s22, v72
	v_sub_u32_e32 v75, v79, v73
	v_cmp_lt_i32_e64 s[0:1], s33, v73
	v_cmp_gt_u32_e32 vcc, s29, v75
	s_or_b64 s[0:1], s[6:7], s[0:1]
	s_and_b64 vcc, vcc, s[0:1]
	v_mul_f32_e32 v75, 0x3fb8aa3b, v96
	v_cndmask_b32_e32 v96, v228, v75, vcc
	v_sub_u32_e32 v75, v73, v79
	v_cmp_lt_i32_e64 s[0:1], s53, v73
	v_cmp_lt_u32_e32 vcc, s28, v75
	s_or_b64 s[0:1], s[6:7], s[0:1]
	s_and_b64 vcc, vcc, s[0:1]
	v_mul_f32_e32 v75, 0x3fb8aa3b, v97
	v_cndmask_b32_e32 v97, v228, v75, vcc
	v_or_b32_e32 v75, 2, v73
	v_sub_u32_e32 v76, v79, v75
	v_cmp_lt_i32_e64 s[0:1], s33, v75
	v_cmp_gt_u32_e32 vcc, s29, v76
	s_or_b64 s[0:1], s[6:7], s[0:1]
	s_and_b64 vcc, vcc, s[0:1]
	v_mul_f32_e32 v75, 0x3fb8aa3b, v98
	v_cndmask_b32_e32 v98, v228, v75, vcc
	v_or_b32_e32 v75, 3, v73
	v_sub_u32_e32 v76, v79, v75
	v_cmp_lt_i32_e64 s[0:1], s33, v75
	v_cmp_gt_u32_e32 vcc, s29, v76
	s_or_b64 s[0:1], s[6:7], s[0:1]
	s_and_b64 vcc, vcc, s[0:1]
	v_mul_f32_e32 v75, 0x3fb8aa3b, v99
	v_or_b32_e32 v76, s18, v72
	v_cndmask_b32_e32 v119, v228, v75, vcc
	v_sub_u32_e32 v75, v79, v76
	v_cmp_lt_i32_e64 s[0:1], s33, v76
	v_cmp_gt_u32_e32 vcc, s29, v75
	s_or_b64 s[0:1], s[6:7], s[0:1]
	s_and_b64 vcc, vcc, s[0:1]
	v_mul_f32_e32 v75, 0x3fb8aa3b, v92
	v_cndmask_b32_e32 v120, v228, v75, vcc
	v_sub_u32_e32 v75, v76, v79
	v_cmp_lt_i32_e64 s[0:1], s53, v76
	v_max3_f32 v0, v80, s49, v81
	v_cmp_lt_u32_e32 vcc, s28, v75
	s_or_b64 s[0:1], s[6:7], s[0:1]
	v_max3_f32 v0, v0, v82, v83
; __device__ __forceinline__ void dilated_item(const Params& p, int item, int next, u32x4 (&pk)[8], u32x4 (&pv)[8], LAS unsigned char* lds) {
;     ...
; #pragma unroll
;     for (int tt = 0; tt < 9; ++tt)
; #pragma unroll
;         for (int rr = 0; rr < 4; ++rr) {
;             const int kj = 16 * (w + tt) + 4 * g + rr, diff = qi - kj;
;             const bool valid = (diff >= 0) && (diff <= 128) && (blk > 0 || kj >= 128);
;             const float s = valid ? sc[tt][rr] * LOG2E : -1e30f;
;             sc[tt][rr] = s; mx = fmaxf(mx, s);
;         }
;     mx = fmaxf(mx, __shfl_xor(mx, 16)); mx = fmaxf(mx, __shfl_xor(mx, 32));
	s_and_b64 vcc, vcc, s[0:1]
	v_mul_f32_e32 v75, 0x3fb8aa3b, v93
	v_max3_f32 v0, v0, v108, v109
	v_cndmask_b32_e32 v121, v228, v75, vcc
	v_or_b32_e32 v75, 2, v76
	v_max3_f32 v0, v0, v110, v111
	v_sub_u32_e32 v92, v79, v75
	v_cmp_lt_i32_e64 s[0:1], s33, v75
	v_max3_f32 v0, v0, v104, v105
	v_cmp_gt_u32_e32 vcc, s29, v92
	s_or_b64 s[0:1], s[6:7], s[0:1]
	v_max3_f32 v0, v0, v106, v107
	s_and_b64 vcc, vcc, s[0:1]
	v_mul_f32_e32 v75, 0x3fb8aa3b, v94
	v_max3_f32 v0, v0, v112, v113
	v_cndmask_b32_e32 v122, v228, v75, vcc
	v_or_b32_e32 v75, 3, v76
	v_max3_f32 v0, v0, v114, v115
	v_sub_u32_e32 v92, v79, v75
	v_cmp_lt_i32_e64 s[0:1], s33, v75
	v_max3_f32 v0, v0, v96, v97
	v_cmp_gt_u32_e32 vcc, s29, v92
	s_or_b64 s[0:1], s[6:7], s[0:1]
	v_max3_f32 v0, v0, v98, v119
	s_and_b64 vcc, vcc, s[0:1]
	v_mul_f32_e32 v75, 0x3fb8aa3b, v95
	v_max3_f32 v0, v0, v120, v121
	v_cndmask_b32_e32 v123, v228, v75, vcc
	v_max3_f32 v75, v0, v122, v123
	v_or_b32_e32 v0, s17, v72
	v_sub_u32_e32 v92, v79, v0
	v_cmp_lt_i32_e64 s[0:1], s33, v0
	v_cmp_gt_u32_e32 vcc, s29, v92
	s_or_b64 s[0:1], s[6:7], s[0:1]
	s_and_b64 vcc, vcc, s[0:1]
	v_sub_u32_e32 v92, v0, v79
	v_cmp_lt_i32_e64 s[0:1], s53, v0
	v_cndmask_b32_e32 v88, v228, v88, vcc
	v_cmp_lt_u32_e32 vcc, s28, v92
	s_or_b64 s[0:1], s[6:7], s[0:1]
	v_or_b32_e32 v92, 2, v0
	s_and_b64 vcc, vcc, s[0:1]
	v_sub_u32_e32 v93, v79, v92
	v_cmp_lt_i32_e64 s[0:1], s33, v92
	v_cndmask_b32_e32 v89, v228, v89, vcc
	v_cmp_gt_u32_e32 vcc, s29, v93
	s_or_b64 s[0:1], s[6:7], s[0:1]
	v_or_b32_e32 v92, 3, v0
	s_and_b64 vcc, vcc, s[0:1]
	v_sub_u32_e32 v93, v79, v92
	v_cmp_lt_i32_e64 s[0:1], s33, v92
	v_cndmask_b32_e32 v90, v228, v90, vcc
	v_cmp_gt_u32_e32 vcc, s29, v93
	s_or_b64 s[0:1], s[6:7], s[0:1]
	s_and_b64 vcc, vcc, s[0:1]
	v_max3_f32 v75, v75, v88, v89
	v_cndmask_b32_e32 v124, v228, v91, vcc
	v_max3_f32 v91, v75, v90, v124
	v_or_b32_e32 v75, s16, v72
	v_sub_u32_e32 v92, v79, v75
	v_cmp_lt_i32_e64 s[0:1], s33, v75
	v_cmp_gt_u32_e32 vcc, s29, v92
	s_or_b64 s[0:1], s[6:7], s[0:1]
	s_and_b64 vcc, vcc, s[0:1]
	v_cndmask_b32_e32 v125, v228, v84, vcc
	v_sub_u32_e32 v84, v75, v79
	v_cmp_lt_i32_e64 s[0:1], s53, v75
	v_cmp_lt_u32_e32 vcc, s28, v84
	s_or_b64 s[0:1], s[6:7], s[0:1]
	s_and_b64 vcc, vcc, s[0:1]
	v_mul_f32_e32 v84, 0x3fb8aa3b, v85
	v_cndmask_b32_e32 v126, v228, v84, vcc
	v_or_b32_e32 v85, 2, v75
	v_max3_f32 v84, v91, v125, v126
	v_sub_u32_e32 v91, v79, v85
	v_cmp_lt_i32_e64 s[0:1], s33, v85
	v_cmp_gt_u32_e32 vcc, s29, v91
	s_or_b64 s[0:1], s[6:7], s[0:1]
	s_and_b64 vcc, vcc, s[0:1]
	v_mul_f32_e32 v85, 0x3fb8aa3b, v86
	v_cndmask_b32_e32 v127, v228, v85, vcc
	v_or_b32_e32 v85, 3, v75
	v_sub_u32_e32 v86, v79, v85
	v_cmp_lt_i32_e64 s[0:1], s33, v85
	v_cmp_gt_u32_e32 vcc, s29, v86
	s_or_b64 s[0:1], s[6:7], s[0:1]
	s_and_b64 vcc, vcc, s[0:1]
	v_mul_f32_e32 v85, 0x3fb8aa3b, v87
	v_or_b32_e32 v72, s15, v72
	v_cndmask_b32_e32 v128, v228, v85, vcc
	v_sub_u32_e32 v85, v79, v72
	v_cmp_lt_i32_e64 s[0:1], s33, v72
	v_cmp_gt_u32_e32 vcc, s29, v85
	s_or_b64 s[0:1], s[6:7], s[0:1]
	s_and_b64 vcc, vcc, s[0:1]
	v_mul_f32_e32 v68, 0x3fb8aa3b, v68
	v_sub_u32_e32 v85, v72, v79
	v_cmp_lt_i32_e64 s[0:1], s53, v72
	v_cndmask_b32_e32 v68, v228, v68, vcc
	v_cmp_lt_u32_e32 vcc, s28, v85
	s_or_b64 s[0:1], s[6:7], s[0:1]
	s_and_b64 vcc, vcc, s[0:1]
	v_mul_f32_e32 v69, 0x3fb8aa3b, v69
	v_max3_f32 v84, v84, v127, v128
	v_cndmask_b32_e32 v129, v228, v69, vcc
	v_max3_f32 v69, v84, v68, v129
	v_or_b32_e32 v84, 2, v72
	v_sub_u32_e32 v85, v79, v84
	v_cmp_lt_i32_e64 s[0:1], s33, v84
	v_cmp_gt_u32_e32 vcc, s29, v85
	s_or_b64 s[0:1], s[6:7], s[0:1]
	v_or_b32_e32 v84, 3, v72
	s_and_b64 vcc, vcc, s[0:1]
	v_mul_f32_e32 v70, 0x3fb8aa3b, v70
	v_sub_u32_e32 v79, v79, v84
	v_cmp_lt_i32_e64 s[0:1], s33, v84
	v_cndmask_b32_e32 v70, v228, v70, vcc
	v_cmp_gt_u32_e32 vcc, s29, v79
	s_or_b64 s[0:1], s[6:7], s[0:1]
	s_and_b64 vcc, vcc, s[0:1]
	v_mul_f32_e32 v71, 0x3fb8aa3b, v71
	v_cndmask_b32_e32 v71, v228, v71, vcc
	v_cmp_lt_i32_e32 vcc, v218, v216
	v_max3_f32 v69, v69, v70, v71
	s_cmp_eq_u32 s4, 1
	v_cndmask_b32_e32 v79, v215, v218, vcc
	v_lshlrev_b32_e32 v130, 2, v79
	ds_bpermute_b32 v79, v130, v69
	v_cmp_lt_i32_e32 vcc, v217, v216
	s_waitcnt lgkmcnt(0)
	v_max_f32_e32 v79, v79, v79
	v_max_f32_e32 v69, v69, v79
	v_cndmask_b32_e32 v79, v215, v217, vcc
	v_lshlrev_b32_e32 v131, 2, v79
	ds_bpermute_b32 v79, v131, v69
	s_waitcnt lgkmcnt(0)
; __device__ __forceinline__ unsigned cvt_pk_bf16(float lo, float hi) { const f32x2v v = {lo, hi}; const b16x2v r = __builtin_convertvector(v, b16x2v); return __builtin_bit_cast(unsigned, r); }
; __device__ __forceinline__ float fexp2(float x) { return __builtin_amdgcn_exp2f(x); }
; __device__ __forceinline__ f32x4 mfma16(bf16x8 a, bf16x8 b, f32x4 c) { return __builtin_amdgcn_mfma_f32_16x16x32_bf16(a, b, c, 0, 0, 0); }
; __device__ __forceinline__ void dilated_item(const Params& p, int item, int next, u32x4 (&pk)[8], u32x4 (&pv)[8], LAS unsigned char* lds) {
;     ...
;     mx = fmaxf(mx, __shfl_xor(mx, 16)); mx = fmaxf(mx, __shfl_xor(mx, 32));
;     float sum = 0.f;
; #pragma unroll
;     for (int tt = 0; tt < 9; ++tt)
; #pragma unroll
;         for (int rr = 0; rr < 4; ++rr) { const float e = fexp2(sc[tt][rr] - mx); sc[tt][rr] = e; sum += e; }
;     sum += __shfl_xor(sum, 16); sum += __shfl_xor(sum, 32);
;     f32x4 ot[8];
; #pragma unroll
;     for (int c = 0; c < 8; ++c) ot[c] = (f32x4){0.f, 0.f, 0.f, 0.f};
; #pragma unroll
;     for (int s5 = 0; s5 < 5; ++s5) {
;         const int ta = w + 2 * s5, tb = (s5 < 4) ? ta + 1 : ta;
;         u32x4 pw; pw.x = cvt_pk_bf16(sc[2 * s5][0], sc[2 * s5][1]); pw.y = cvt_pk_bf16(sc[2 * s5][2], sc[2 * s5][3]);
;         if (s5 < 4) { pw.z = cvt_pk_bf16(sc[(2 * s5 + 1) % 9][0], sc[(2 * s5 + 1) % 9][1]); pw.w = cvt_pk_bf16(sc[(2 * s5 + 1) % 9][2], sc[(2 * s5 + 1) % 9][3]); } else { pw.z = 0u; pw.w = 0u; }
;         const bf16x8 pf = __builtin_bit_cast(bf16x8, pw);
;         const unsigned aA = lbase + KV_BUF + (unsigned)((16 * ta + 4 * g + (idx >> 2)) * KV_STRIDE + 8 * (idx & 3));
;         const unsigned aB = lbase + KV_BUF + (unsigned)((16 * tb + 4 * g + (idx >> 2)) * KV_STRIDE + 8 * (idx & 3));
;         bf16x8 vf[4];
;         tr_frag4(aA, aB, vf);
; #pragma unroll
;         for (int c = 0; c < 4; ++c) ot[c] = mfma16(vf[c], pf, ot[c]);
;         tr_frag4(aA + 128, aB + 128, vf);
; #pragma unroll
;         for (int c = 0; c < 4; ++c) ot[4 + c] = mfma16(vf[c], pf, ot[4 + c]);
	v_max_f32_e32 v79, v79, v79
	v_max_f32_e32 v69, v69, v79
	v_sub_f32_e32 v79, v80, v69
	v_exp_f32_e32 v132, v79
	v_sub_f32_e32 v80, v81, v69
	v_exp_f32_e32 v133, v80
	v_sub_f32_e32 v80, v82, v69
	v_exp_f32_e32 v134, v80
	v_sub_f32_e32 v80, v83, v69
	v_exp_f32_e32 v135, v80
	v_sub_f32_e32 v80, v108, v69
	v_add_f32_e32 v79, 0, v132
	v_exp_f32_e32 v136, v80
	v_sub_f32_e32 v80, v109, v69
	v_add_f32_e32 v79, v133, v79
	v_exp_f32_e32 v137, v80
	v_sub_f32_e32 v80, v110, v69
	v_add_f32_e32 v79, v134, v79
	v_exp_f32_e32 v138, v80
	v_sub_f32_e32 v80, v111, v69
	v_add_f32_e32 v79, v135, v79
	v_exp_f32_e32 v111, v80
	v_sub_f32_e32 v80, v104, v69
	v_add_f32_e32 v79, v136, v79
	v_exp_f32_e32 v99, v80
	v_sub_f32_e32 v80, v105, v69
	v_add_f32_e32 v79, v137, v79
	v_exp_f32_e32 v100, v80
	v_sub_f32_e32 v80, v106, v69
	v_add_f32_e32 v79, v138, v79
	v_exp_f32_e32 v101, v80
	v_sub_f32_e32 v80, v107, v69
	v_add_f32_e32 v79, v111, v79
	v_exp_f32_e32 v102, v80
	v_sub_f32_e32 v80, v112, v69
	v_add_f32_e32 v79, v99, v79
	v_exp_f32_e32 v103, v80
	v_sub_f32_e32 v80, v113, v69
	v_add_f32_e32 v79, v100, v79
	v_exp_f32_e32 v104, v80
	v_sub_f32_e32 v80, v114, v69
	v_add_f32_e32 v79, v101, v79
	v_exp_f32_e32 v105, v80
	v_sub_f32_e32 v80, v115, v69
	v_add_f32_e32 v79, v102, v79
	v_exp_f32_e32 v106, v80
	v_sub_f32_e32 v80, v96, v69
	v_add_f32_e32 v79, v103, v79
	v_exp_f32_e32 v91, v80
	v_sub_f32_e32 v80, v97, v69
	v_add_f32_e32 v79, v104, v79
	v_exp_f32_e32 v92, v80
	v_sub_f32_e32 v80, v98, v69
	v_add_f32_e32 v79, v105, v79
	v_exp_f32_e32 v93, v80
	v_sub_f32_e32 v80, v119, v69
	v_add_f32_e32 v79, v106, v79
	v_exp_f32_e32 v94, v80
	v_sub_f32_e32 v80, v120, v69
	v_add_f32_e32 v79, v91, v79
	v_exp_f32_e32 v95, v80
	v_sub_f32_e32 v80, v121, v69
	v_add_f32_e32 v79, v92, v79
	v_exp_f32_e32 v96, v80
	v_sub_f32_e32 v80, v122, v69
	v_add_f32_e32 v79, v93, v79
	v_exp_f32_e32 v97, v80
	v_sub_f32_e32 v80, v123, v69
	v_add_f32_e32 v79, v94, v79
	v_exp_f32_e32 v98, v80
	v_sub_f32_e32 v80, v88, v69
	v_add_f32_e32 v79, v95, v79
	v_exp_f32_e32 v83, v80
	v_sub_f32_e32 v80, v89, v69
	v_add_f32_e32 v79, v96, v79
	v_exp_f32_e32 v84, v80
	v_sub_f32_e32 v80, v90, v69
	v_add_f32_e32 v79, v97, v79
	v_exp_f32_e32 v85, v80
	v_sub_f32_e32 v80, v124, v69
	v_add_f32_e32 v79, v98, v79
	v_exp_f32_e32 v86, v80
	v_sub_f32_e32 v80, v125, v69
	v_add_f32_e32 v79, v83, v79
	v_exp_f32_e32 v87, v80
	v_sub_f32_e32 v80, v126, v69
	v_add_f32_e32 v79, v84, v79
	v_exp_f32_e32 v88, v80
	v_sub_f32_e32 v80, v127, v69
	v_add_f32_e32 v79, v85, v79
	v_exp_f32_e32 v89, v80
	v_sub_f32_e32 v80, v128, v69
	v_add_f32_e32 v79, v86, v79
	v_exp_f32_e32 v90, v80
	v_add_f32_e32 v79, v87, v79
	v_add_f32_e32 v79, v88, v79
	v_add_f32_e32 v79, v89, v79
	v_sub_f32_e32 v68, v68, v69
	v_add_f32_e32 v80, v90, v79
	v_exp_f32_e32 v79, v68
	v_sub_f32_e32 v70, v70, v69
	v_exp_f32_e32 v81, v70
	v_sub_f32_e32 v70, v71, v69
	v_add_f32_e32 v68, v79, v80
	v_sub_f32_e32 v80, v129, v69
	v_exp_f32_e32 v80, v80
	v_exp_f32_e32 v82, v70
	v_lshrrev_b32_e32 v107, 2, v118
	v_cvt_pk_bf16_f32 v108, v132, v133
	v_add_f32_e32 v68, v80, v68
	v_add_f32_e32 v68, v81, v68
	v_add_f32_e32 v68, v82, v68
	ds_bpermute_b32 v70, v130, v68
	v_cvt_pk_bf16_f32 v109, v134, v135
	v_cvt_pk_bf16_f32 v110, v136, v137
	v_cvt_pk_bf16_f32 v111, v138, v111
	v_cvt_pk_bf16_f32 v101, v101, v102
	s_waitcnt lgkmcnt(0)
	v_add_f32_e32 v70, v68, v70
	v_and_b32_e32 v68, 24, v1
	v_or_b32_e32 v1, v2, v107
	v_or_b32_e32 v2, v78, v107
	ds_bpermute_b32 v71, v131, v70
	v_mad_u64_u32 v[130:131], s[0:1], v1, s99, v[68:69]
	v_mad_u64_u32 v[132:133], s[0:1], v2, s99, v[68:69]
	v_add_u32_e32 v1, s11, v130
	v_add_u32_e32 v2, s11, v132
	ds_read_b64_tr_b16 v[126:127], v1
	ds_read_b64_tr_b16 v[122:123], v1 offset:32
	ds_read_b64_tr_b16 v[118:119], v1 offset:64
	ds_read_b64_tr_b16 v[112:113], v1 offset:96
	ds_read_b64_tr_b16 v[128:129], v2
	ds_read_b64_tr_b16 v[124:125], v2 offset:32
	ds_read_b64_tr_b16 v[120:121], v2 offset:64
	ds_read_b64_tr_b16 v[114:115], v2 offset:96
	s_waitcnt lgkmcnt(0)
	v_add_u32_e32 v1, s14, v130
	v_mfma_f32_16x16x32_bf16 v[126:129], v[126:129], v[108:111], 0
	v_add_u32_e32 v2, s14, v132
	ds_read_b64_tr_b16 v[142:143], v1
	ds_read_b64_tr_b16 v[138:139], v1 offset:32
	ds_read_b64_tr_b16 v[134:135], v1 offset:64
	ds_read_b64_tr_b16 v[130:131], v1 offset:96
	ds_read_b64_tr_b16 v[144:145], v2
	ds_read_b64_tr_b16 v[140:141], v2 offset:32
	ds_read_b64_tr_b16 v[136:137], v2 offset:64
	ds_read_b64_tr_b16 v[132:133], v2 offset:96
	s_waitcnt lgkmcnt(0)
	v_or_b32_e32 v1, v74, v107
	v_mfma_f32_16x16x32_bf16 v[122:125], v[122:125], v[108:111], 0
	v_or_b32_e32 v2, v77, v107
	v_cvt_pk_bf16_f32 v102, v103, v104
	v_cvt_pk_bf16_f32 v103, v105, v106
	v_mfma_f32_16x16x32_bf16 v[118:121], v[118:121], v[108:111], 0
	v_mad_u64_u32 v[104:105], s[0:1], v1, s99, v[68:69]
	v_mad_u64_u32 v[158:159], s[0:1], v2, s99, v[68:69]
	v_mfma_f32_16x16x32_bf16 v[112:115], v[112:115], v[108:111], 0
	v_cvt_pk_bf16_f32 v100, v99, v100
	v_add_u32_e32 v1, s11, v104
	v_add_u32_e32 v2, s11, v158
	v_mfma_f32_16x16x32_bf16 v[142:145], v[142:145], v[108:111], 0
	v_cvt_pk_bf16_f32 v92, v91, v92
	v_cvt_pk_bf16_f32 v93, v93, v94
	v_cvt_pk_bf16_f32 v94, v95, v96
	v_mfma_f32_16x16x32_bf16 v[138:141], v[138:141], v[108:111], 0
	v_cvt_pk_bf16_f32 v95, v97, v98
	v_or_b32_e32 v0, v0, v107
	v_cvt_pk_bf16_f32 v84, v83, v84
	v_mfma_f32_16x16x32_bf16 v[134:137], v[134:137], v[108:111], 0
	v_cvt_pk_bf16_f32 v85, v85, v86
	v_cvt_pk_bf16_f32 v86, v87, v88
	v_cvt_pk_bf16_f32 v87, v89, v90
	v_mfma_f32_16x16x32_bf16 v[108:111], v[130:133], v[108:111], 0
	ds_read_b64_tr_b16 v[154:155], v1
	ds_read_b64_tr_b16 v[150:151], v1 offset:32
	ds_read_b64_tr_b16 v[146:147], v1 offset:64
	ds_read_b64_tr_b16 v[130:131], v1 offset:96
	ds_read_b64_tr_b16 v[156:157], v2
	ds_read_b64_tr_b16 v[152:153], v2 offset:32
	ds_read_b64_tr_b16 v[148:149], v2 offset:64
	ds_read_b64_tr_b16 v[132:133], v2 offset:96
	s_waitcnt lgkmcnt(0)
; __device__ __forceinline__ unsigned cvt_pk_bf16(float lo, float hi) { const f32x2v v = {lo, hi}; const b16x2v r = __builtin_convertvector(v, b16x2v); return __builtin_bit_cast(unsigned, r); }
; __device__ __forceinline__ f32x4 mfma16(bf16x8 a, bf16x8 b, f32x4 c) { return __builtin_amdgcn_mfma_f32_16x16x32_bf16(a, b, c, 0, 0, 0); }
; __device__ __forceinline__ void dilated_item(const Params& p, int item, int next, u32x4 (&pk)[8], u32x4 (&pv)[8], LAS unsigned char* lds) {
;     ...
;     for (int s5 = 0; s5 < 5; ++s5) {
;         const int ta = w + 2 * s5, tb = (s5 < 4) ? ta + 1 : ta;
;         u32x4 pw; pw.x = cvt_pk_bf16(sc[2 * s5][0], sc[2 * s5][1]); pw.y = cvt_pk_bf16(sc[2 * s5][2], sc[2 * s5][3]);
;         if (s5 < 4) { pw.z = cvt_pk_bf16(sc[(2 * s5 + 1) % 9][0], sc[(2 * s5 + 1) % 9][1]); pw.w = cvt_pk_bf16(sc[(2 * s5 + 1) % 9][2], sc[(2 * s5 + 1) % 9][3]); } else { pw.z = 0u; pw.w = 0u; }
;         const bf16x8 pf = __builtin_bit_cast(bf16x8, pw);
;         const unsigned aA = lbase + KV_BUF + (unsigned)((16 * ta + 4 * g + (idx >> 2)) * KV_STRIDE + 8 * (idx & 3));
;         const unsigned aB = lbase + KV_BUF + (unsigned)((16 * tb + 4 * g + (idx >> 2)) * KV_STRIDE + 8 * (idx & 3));
;         bf16x8 vf[4];
;         tr_frag4(aA, aB, vf);
; #pragma unroll
;         for (int c = 0; c < 4; ++c) ot[c] = mfma16(vf[c], pf, ot[c]);
;         tr_frag4(aA + 128, aB + 128, vf);
; #pragma unroll
;         for (int c = 0; c < 4; ++c) ot[4 + c] = mfma16(vf[c], pf, ot[4 + c]);
	v_add_u32_e32 v1, s14, v104
	v_add_u32_e32 v2, s14, v158
	v_mfma_f32_16x16x32_bf16 v[126:129], v[154:157], v[100:103], v[126:129]
	v_or_b32_e32 v72, v72, v107
	v_mfma_f32_16x16x32_bf16 v[122:125], v[150:153], v[100:103], v[122:125]
	v_mfma_f32_16x16x32_bf16 v[118:121], v[146:149], v[100:103], v[118:121]
	v_mfma_f32_16x16x32_bf16 v[112:115], v[130:133], v[100:103], v[112:115]
	ds_read_b64_tr_b16 v[154:155], v1
	ds_read_b64_tr_b16 v[150:151], v1 offset:32
	ds_read_b64_tr_b16 v[146:147], v1 offset:64
	ds_read_b64_tr_b16 v[130:131], v1 offset:96
	ds_read_b64_tr_b16 v[156:157], v2
	ds_read_b64_tr_b16 v[152:153], v2 offset:32
	ds_read_b64_tr_b16 v[148:149], v2 offset:64
	ds_read_b64_tr_b16 v[132:133], v2 offset:96
	s_waitcnt lgkmcnt(0)
	v_or_b32_e32 v1, v73, v107
	v_or_b32_e32 v2, v76, v107
	v_mfma_f32_16x16x32_bf16 v[142:145], v[154:157], v[100:103], v[142:145]
	v_mad_u64_u32 v[104:105], s[0:1], v1, s99, v[68:69]
	v_mad_u64_u32 v[76:77], s[0:1], v2, s99, v[68:69]
	v_mfma_f32_16x16x32_bf16 v[138:141], v[150:153], v[100:103], v[138:141]
	v_add_u32_e32 v1, s11, v104
	v_add_u32_e32 v2, s11, v76
	v_mfma_f32_16x16x32_bf16 v[134:137], v[146:149], v[100:103], v[134:137]
	v_mfma_f32_16x16x32_bf16 v[100:103], v[130:133], v[100:103], v[108:111]
	ds_read_b64_tr_b16 v[146:147], v1
	ds_read_b64_tr_b16 v[130:131], v1 offset:32
	ds_read_b64_tr_b16 v[108:109], v1 offset:64
	ds_read_b64_tr_b16 v[96:97], v1 offset:96
	ds_read_b64_tr_b16 v[148:149], v2
	ds_read_b64_tr_b16 v[132:133], v2 offset:32
	ds_read_b64_tr_b16 v[110:111], v2 offset:64
	ds_read_b64_tr_b16 v[98:99], v2 offset:96
	s_waitcnt lgkmcnt(0)
	v_add_u32_e32 v1, s14, v104
	v_add_u32_e32 v2, s14, v76
	v_mfma_f32_16x16x32_bf16 v[126:129], v[146:149], v[92:95], v[126:129]
	v_mfma_f32_16x16x32_bf16 v[122:125], v[130:133], v[92:95], v[122:125]
	v_mfma_f32_16x16x32_bf16 v[108:111], v[108:111], v[92:95], v[118:121]
	v_mfma_f32_16x16x32_bf16 v[96:99], v[96:99], v[92:95], v[112:115]
	ds_read_b64_tr_b16 v[146:147], v1
	ds_read_b64_tr_b16 v[130:131], v1 offset:32
	ds_read_b64_tr_b16 v[118:119], v1 offset:64
	ds_read_b64_tr_b16 v[112:113], v1 offset:96
	ds_read_b64_tr_b16 v[148:149], v2
	ds_read_b64_tr_b16 v[132:133], v2 offset:32
	ds_read_b64_tr_b16 v[120:121], v2 offset:64
	ds_read_b64_tr_b16 v[114:115], v2 offset:96
	s_waitcnt lgkmcnt(0)
	v_or_b32_e32 v2, v75, v107
	v_mad_u64_u32 v[0:1], s[0:1], v0, s99, v[68:69]
	v_mfma_f32_16x16x32_bf16 v[142:145], v[146:149], v[92:95], v[142:145]
	v_mad_u64_u32 v[104:105], s[0:1], v2, s99, v[68:69]
	v_add_u32_e32 v1, s11, v0
	v_mfma_f32_16x16x32_bf16 v[130:133], v[130:133], v[92:95], v[138:141]
	v_add_u32_e32 v2, s11, v104
	v_add_u32_e32 v0, s14, v0
	v_mfma_f32_16x16x32_bf16 v[118:121], v[118:121], v[92:95], v[134:137]
	v_mfma_f32_16x16x32_bf16 v[92:95], v[112:115], v[92:95], v[100:103]
	ds_read_b64_tr_b16 v[112:113], v1
	ds_read_b64_tr_b16 v[100:101], v1 offset:32
	ds_read_b64_tr_b16 v[88:89], v1 offset:64
	ds_read_b64_tr_b16 v[74:75], v1 offset:96
	ds_read_b64_tr_b16 v[114:115], v2
	ds_read_b64_tr_b16 v[102:103], v2 offset:32
	ds_read_b64_tr_b16 v[90:91], v2 offset:64
	ds_read_b64_tr_b16 v[76:77], v2 offset:96
	s_waitcnt lgkmcnt(0)
	v_add_u32_e32 v1, s14, v104
	v_mov_b32_e32 v2, v3
	v_mfma_f32_16x16x32_bf16 v[112:115], v[112:115], v[84:87], v[126:129]
	v_mfma_f32_16x16x32_bf16 v[100:103], v[100:103], v[84:87], v[122:125]
	v_mfma_f32_16x16x32_bf16 v[88:91], v[88:91], v[84:87], v[108:111]
	v_mfma_f32_16x16x32_bf16 v[74:77], v[74:77], v[84:87], v[96:99]
	ds_read_b64_tr_b16 v[126:127], v0
	ds_read_b64_tr_b16 v[122:123], v0 offset:32
	ds_read_b64_tr_b16 v[108:109], v0 offset:64
	ds_read_b64_tr_b16 v[96:97], v0 offset:96
	ds_read_b64_tr_b16 v[128:129], v1
	ds_read_b64_tr_b16 v[124:125], v1 offset:32
	ds_read_b64_tr_b16 v[110:111], v1 offset:64
	ds_read_b64_tr_b16 v[98:99], v1 offset:96
	s_waitcnt lgkmcnt(0)
	v_cvt_pk_bf16_f32 v1, v81, v82
	v_mad_u64_u32 v[82:83], s[0:1], v72, s99, v[68:69]
	v_mfma_f32_16x16x32_bf16 v[126:129], v[126:129], v[84:87], v[142:145]
	v_add_u32_e32 v68, s11, v82
	v_cvt_pk_bf16_f32 v0, v79, v80
	v_mfma_f32_16x16x32_bf16 v[122:125], v[122:125], v[84:87], v[130:133]
	v_mfma_f32_16x16x32_bf16 v[108:111], v[108:111], v[84:87], v[118:121]
	v_mfma_f32_16x16x32_bf16 v[84:87], v[96:99], v[84:87], v[92:95]
	ds_read_b64_tr_b16 v[104:105], v68
	ds_read_b64_tr_b16 v[96:97], v68 offset:32
	ds_read_b64_tr_b16 v[92:93], v68 offset:64
	ds_read_b64_tr_b16 v[78:79], v68 offset:96
	ds_read_b64_tr_b16 v[106:107], v68
	ds_read_b64_tr_b16 v[98:99], v68 offset:32
	ds_read_b64_tr_b16 v[94:95], v68 offset:64
	ds_read_b64_tr_b16 v[80:81], v68 offset:96
	s_waitcnt lgkmcnt(0)
; __device__ __forceinline__ unsigned cvt_pk_bf16(float lo, float hi) { const f32x2v v = {lo, hi}; const b16x2v r = __builtin_convertvector(v, b16x2v); return __builtin_bit_cast(unsigned, r); }
; __device__ __forceinline__ float flog2(float x) { return __builtin_amdgcn_logf(x); }
; __device__ __forceinline__ f32x4 mfma16(bf16x8 a, bf16x8 b, f32x4 c) { return __builtin_amdgcn_mfma_f32_16x16x32_bf16(a, b, c, 0, 0, 0); }
; __device__ __forceinline__ void dilated_item(const Params& p, int item, int next, u32x4 (&pk)[8], u32x4 (&pv)[8], LAS unsigned char* lds) {
;     ...
;         for (int c = 0; c < 4; ++c) ot[4 + c] = mfma16(vf[c], pf, ot[4 + c]);
;     }
;     const float inv = 1.0f / sum;
;     const size_t tok = (size_t)(b * SEQ + qpos);
;     bf16_t* od = (bf16_t*)(ws + (pat == 0 ? OFF_B2 : (pat == 1 ? OFF_B2 + 32 * MiB : OFF_OD2)));
; #pragma unroll
;     for (int c = 0; c < 8; ++c) { u32x2 wv; wv.x = cvt_pk_bf16(ot[c][0] * inv, ot[c][1] * inv); wv.y = cvt_pk_bf16(ot[c][2] * inv, ot[c][3] * inv);
;         *(u32x2*)(od + tok * 1024 + head * 128 + 16 * c + 4 * g) = wv; }
;     if (g == 0) ((float*)(ws + OFF_LSE))[(size_t)pat * T_TOK * 8 + tok * 8 + head] = (mx + flog2(sum)) * LN2;
	v_add_u32_e32 v68, s14, v82
	v_mfma_f32_16x16x32_bf16 v[96:99], v[96:99], v[0:3], v[100:103]
	v_mfma_f32_16x16x32_bf16 v[88:91], v[92:95], v[0:3], v[88:91]
	v_mfma_f32_16x16x32_bf16 v[72:75], v[78:81], v[0:3], v[74:77]
	ds_read_b64_tr_b16 v[100:101], v68
	ds_read_b64_tr_b16 v[92:93], v68 offset:32
	ds_read_b64_tr_b16 v[80:81], v68 offset:64
	ds_read_b64_tr_b16 v[76:77], v68 offset:96
	ds_read_b64_tr_b16 v[102:103], v68
	ds_read_b64_tr_b16 v[94:95], v68 offset:32
	ds_read_b64_tr_b16 v[82:83], v68 offset:64
	ds_read_b64_tr_b16 v[78:79], v68 offset:96
	s_waitcnt lgkmcnt(0)
	s_waitcnt lgkmcnt(0)
	v_add_f32_e32 v68, v70, v71
	v_mfma_f32_16x16x32_bf16 v[104:107], v[104:107], v[0:3], v[112:115]
	v_mfma_f32_16x16x32_bf16 v[100:103], v[100:103], v[0:3], v[126:129]
	v_mfma_f32_16x16x32_bf16 v[92:95], v[92:95], v[0:3], v[122:125]
	v_mfma_f32_16x16x32_bf16 v[80:83], v[80:83], v[0:3], v[108:111]
	v_mfma_f32_16x16x32_bf16 v[76:79], v[76:79], v[0:3], v[84:87]
	v_div_scale_f32 v0, s[0:1], v68, v68, 1.0
	v_rcp_f32_e32 v1, v0
	s_mov_b32 s0, 0x6000000
	s_cselect_b32 s0, s0, 0x1b100000
	s_cmpk_gt_u32 s8, 0x3ff
	v_fma_f32 v2, -v0, v1, 1.0
	v_fmac_f32_e32 v1, v2, v1
	v_div_scale_f32 v2, vcc, 1.0, v68, 1.0
	v_mul_f32_e32 v70, v2, v1
	v_fma_f32 v71, -v0, v70, v2
	v_fmac_f32_e32 v70, v71, v1
	v_fma_f32 v0, -v0, v70, v2
	v_div_fmas_f32 v0, v0, v1, v70
	v_div_fixup_f32 v70, v0, v68, 1.0
	v_add_u32_e32 v0, s5, v117
	s_cselect_b32 s0, s0, 0x4000000
	v_ashrrev_i32_e32 v1, 31, v0
	s_add_u32 s0, s92, s0
	s_addc_u32 s1, s93, 0
	v_lshlrev_b64 v[84:85], 11, v[0:1]
	v_lshl_add_u64 v[84:85], s[0:1], 0, v[84:85]
	s_lshl_b32 s18, s12, 1
	v_lshl_add_u64 v[84:85], v[84:85], 0, s[18:19]
	v_lshlrev_b32_e32 v2, 3, v116
	v_lshl_add_u64 v[84:85], v[84:85], 0, v[2:3]
	v_and_b32_e32 v2, 1, v116
	v_mul_u32_u24_e32 v2, 24, v2
	v_lshl_add_u64 v[86:87], v[84:85], 0, v[2:3]
	v_pk_mul_f32 v[88:89], v[70:71], v[88:89] op_sel_hi:[0,1]
	v_pk_mul_f32 v[90:91], v[70:71], v[90:91] op_sel_hi:[0,1]
	v_pk_mul_f32 v[72:73], v[70:71], v[72:73] op_sel_hi:[0,1]
	v_pk_mul_f32 v[74:75], v[70:71], v[74:75] op_sel_hi:[0,1]
	v_cvt_pk_bf16_f32 v88, v88, v89
	v_cvt_pk_bf16_f32 v89, v90, v91
	v_cvt_pk_bf16_f32 v90, v72, v73
	v_cvt_pk_bf16_f32 v91, v74, v75
	s_nop 1
	v_permlane16_swap_b32 v88, v90
	v_permlane16_swap_b32 v89, v91
	global_store_dwordx4 v[86:87], v[88:91], off offset:64
	v_pk_mul_f32 v[104:105], v[70:71], v[104:105] op_sel_hi:[0,1]
	v_pk_mul_f32 v[106:107], v[70:71], v[106:107] op_sel_hi:[0,1]
	v_pk_mul_f32 v[96:97], v[70:71], v[96:97] op_sel_hi:[0,1]
	v_pk_mul_f32 v[98:99], v[70:71], v[98:99] op_sel_hi:[0,1]
	v_cvt_pk_bf16_f32 v104, v104, v105
	v_cvt_pk_bf16_f32 v105, v106, v107
	v_cvt_pk_bf16_f32 v106, v96, v97
	v_cvt_pk_bf16_f32 v107, v98, v99
	s_nop 1
	v_permlane16_swap_b32 v104, v106
	v_permlane16_swap_b32 v105, v107
	global_store_dwordx4 v[86:87], v[104:107], off
	v_pk_mul_f32 v[100:101], v[70:71], v[100:101] op_sel_hi:[0,1]
	v_pk_mul_f32 v[102:103], v[70:71], v[102:103] op_sel_hi:[0,1]
	v_pk_mul_f32 v[92:93], v[70:71], v[92:93] op_sel_hi:[0,1]
	v_pk_mul_f32 v[94:95], v[70:71], v[94:95] op_sel_hi:[0,1]
	v_cvt_pk_bf16_f32 v100, v100, v101
	v_cvt_pk_bf16_f32 v101, v102, v103
	v_cvt_pk_bf16_f32 v102, v92, v93
	v_cvt_pk_bf16_f32 v103, v94, v95
	s_nop 1
	v_permlane16_swap_b32 v100, v102
	v_permlane16_swap_b32 v101, v103
	global_store_dwordx4 v[86:87], v[100:103], off offset:128
	v_pk_mul_f32 v[80:81], v[70:71], v[80:81] op_sel_hi:[0,1]
	v_pk_mul_f32 v[82:83], v[70:71], v[82:83] op_sel_hi:[0,1]
	v_pk_mul_f32 v[76:77], v[70:71], v[76:77] op_sel_hi:[0,1]
	v_pk_mul_f32 v[78:79], v[70:71], v[78:79] op_sel_hi:[0,1]
	v_cvt_pk_bf16_f32 v80, v80, v81
	v_cvt_pk_bf16_f32 v81, v82, v83
	v_cvt_pk_bf16_f32 v82, v76, v77
	v_cvt_pk_bf16_f32 v83, v78, v79
	s_nop 1
	v_permlane16_swap_b32 v80, v82
	v_permlane16_swap_b32 v81, v83
	global_store_dwordx4 v[86:87], v[80:83], off offset:192
	v_cmp_eq_u32_e32 vcc, 0, v116
	s_and_saveexec_b64 s[0:1], vcc
	s_cbranch_execz .LBB0_432
	v_log_f32_e32 v2, v68
	s_ashr_i32 s5, s4, 31
	s_lshl_b64 s[4:5], s[4:5], 19
	v_readlane_b32 s6, v251, 28
	v_readlane_b32 s7, v251, 29
	s_add_u32 s4, s6, s4
	s_addc_u32 s5, s7, s5
	v_lshlrev_b64 v[0:1], 5, v[0:1]
	v_add_f32_e32 v2, v69, v2
	v_lshl_add_u64 v[0:1], s[4:5], 0, v[0:1]
	s_lshl_b32 s18, s9, 2
	v_mul_f32_e32 v2, 0x3f317218, v2
	v_lshl_add_u64 v[0:1], v[0:1], 0, s[18:19]
	global_store_dword v[0:1], v2, off
	s_branch .LBB0_432
